# non-temporal hint on GEMM and attention epilogue stores and on the residual-stream loads of the output projections
# baseline (speedup 1.0000x reference)
.LBB0_700:
	s_or_b64 exec, exec, s[6:7]
	v_cvt_pk_bf16_f32 v126, v126, v127
	v_cvt_pk_bf16_f32 v127, v128, v129
	v_cvt_pk_bf16_f32 v128, v122, v123
	v_mov_b64_e32 v[122:123], s[16:17]
	v_mad_u64_u32 v[122:123], s[6:7], v154, s73, v[122:123]
	v_mad_i32_i24 v123, v155, s73, v123
	v_ashrrev_i32_e32 v149, 31, v148
	v_cvt_pk_bf16_f32 v129, v124, v125
	v_lshl_add_u64 v[124:125], v[148:149], 1, v[122:123]
	global_store_dwordx4 v[124:125], v[126:129], off nt
	v_mov_b32_e32 v157, v156
	v_pk_mul_f32 v[118:119], v[118:119], v[156:157]
	v_or_b32_e32 v128, 0x80, v148
	v_mov_b32_e32 v126, v156
	v_mov_b32_e32 v127, v156
	v_pk_mul_f32 v[120:121], v[120:121], v[126:127]
	v_pk_mul_f32 v[116:117], v[116:117], v[126:127]
	v_mul_hi_i32 v126, v128, s64
	v_lshrrev_b32_e32 v127, 31, v126
	v_lshrrev_b32_e32 v126, 5, v126
	v_add_u32_e32 v126, v126, v127
	v_mul_lo_u32 v126, v126, s70
	v_sub_u32_e32 v126, v128, v126
	v_cmp_lt_i32_e32 vcc, s71, v126
	v_pk_mul_f32 v[114:115], v[114:115], v[156:157]
	s_and_b64 s[42:43], s[46:47], vcc
	v_and_b32_e32 v127, 24, v126
	s_and_saveexec_b64 s[6:7], s[42:43]
	s_cbranch_execz .LBB0_702
	v_mov_b32_e32 v128, s31
	v_cmp_gt_u32_e32 vcc, s72, v126
	s_nop 1
	v_cndmask_b32_e32 v128, v159, v128, vcc
	v_lshl_or_b32 v128, v128, 5, v127
	v_ashrrev_i32_e32 v129, 31, v128
	v_lshl_add_u64 v[128:129], v[128:129], 2, s[18:19]
	global_load_dwordx4 v[154:157], v[128:129], off
	global_load_dwordx4 v[178:181], v[128:129], off offset:16
	s_waitcnt vmcnt(1)
	v_pk_mul_f32 v[182:183], v[118:119], v[154:155] op_sel:[1,1] op_sel_hi:[1,0]
	v_mul_f32_e32 v184, v121, v157
	v_mul_f32_e32 v186, v121, v156
	s_waitcnt vmcnt(0)
	v_pk_mul_f32 v[190:191], v[114:115], v[178:179] op_sel:[1,1] op_sel_hi:[1,0]
	v_mul_f32_e32 v192, v117, v181
	v_mul_f32_e32 v194, v117, v180
	v_pk_mul_f32 v[128:129], v[118:119], v[154:155]
	v_pk_mul_f32 v[188:189], v[114:115], v[178:179]
	v_pk_fma_f32 v[118:119], v[118:119], v[154:155], v[182:183] op_sel_hi:[0,1,1]
	v_pk_fma_f32 v[154:155], v[120:121], v[156:157], v[184:185] op_sel_hi:[1,1,0] neg_lo:[0,0,1] neg_hi:[0,0,1]
	v_pk_fma_f32 v[156:157], v[120:121], v[156:157], v[186:187] op_sel:[0,1,0] op_sel_hi:[1,0,0]
	v_pk_fma_f32 v[114:115], v[114:115], v[178:179], v[190:191] op_sel_hi:[0,1,1]
	v_pk_fma_f32 v[120:121], v[116:117], v[180:181], v[192:193] op_sel_hi:[1,1,0] neg_lo:[0,0,1] neg_hi:[0,0,1]
	v_pk_fma_f32 v[178:179], v[116:117], v[180:181], v[194:195] op_sel:[0,1,0] op_sel_hi:[1,0,0]
	v_sub_f32_e32 v114, v188, v190
	v_sub_f32_e32 v118, v128, v182
	v_mov_b32_e32 v116, v120
	v_mov_b32_e32 v117, v178
	v_mov_b32_e32 v120, v154
	v_mov_b32_e32 v121, v156
.LBB0_702:
	s_or_b64 exec, exec, s[6:7]
	v_cvt_pk_bf16_f32 v118, v118, v119
	v_cvt_pk_bf16_f32 v119, v120, v121
	v_cvt_pk_bf16_f32 v120, v114, v115
	v_or_b32_e32 v114, 0x200, v152
	v_mov_b32_e32 v115, v153
	v_cvt_pk_bf16_f32 v121, v116, v117
	global_store_dwordx4 v[124:125], v[118:121], off offset:256 nt
	v_lshl_add_u64 v[114:115], s[12:13], 0, v[114:115]
	global_load_dwordx4 v[114:117], v[114:115], off
	s_waitcnt vmcnt(0)
	v_mov_b32_e32 v118, v115
	v_mov_b32_e32 v119, v116
	v_mov_b32_e32 v115, v117
	v_pk_add_f32 v[114:115], v[118:119], v[114:115]
	s_nop 0
	v_add_f32_e32 v114, v114, v115
	v_fmamk_f32 v114, v114, 0x3a800000, v173
	v_mul_f32_e32 v115, 0x4f800000, v114
	v_cmp_gt_f32_e32 vcc, s69, v114
	s_nop 1
	v_cndmask_b32_e32 v114, v114, v115, vcc
	v_sqrt_f32_e32 v115, v114
	s_nop 0
	v_add_u32_e32 v116, -1, v115
	v_add_u32_e32 v117, 1, v115
	v_fma_f32 v118, -v116, v115, v114
	v_fma_f32 v119, -v117, v115, v114
	v_cmp_ge_f32_e64 s[6:7], 0, v118
	s_nop 1
	v_cndmask_b32_e64 v115, v115, v116, s[6:7]
	v_cmp_lt_f32_e64 s[6:7], 0, v119
	s_nop 1
	v_cndmask_b32_e64 v115, v115, v117, s[6:7]
	v_mul_f32_e32 v116, 0x37800000, v115
	v_cndmask_b32_e32 v115, v115, v116, vcc
	v_cmp_class_f32_e32 vcc, v114, v174
	s_nop 1
	v_cndmask_b32_e32 v114, v115, v114, vcc
	v_div_scale_f32 v115, s[6:7], v114, v114, 1.0
	v_rcp_f32_e32 v116, v115
	v_div_scale_f32 v117, vcc, 1.0, v114, 1.0
	v_fma_f32 v118, -v115, v116, 1.0
	v_fmac_f32_e32 v116, v118, v116
	v_mul_f32_e32 v118, v117, v116
	v_fma_f32 v119, -v115, v118, v117
	v_fmac_f32_e32 v118, v119, v116
	v_fma_f32 v115, -v115, v118, v117
	v_div_fmas_f32 v115, v115, v116, v118
	v_div_fixup_f32 v114, v115, v114, 1.0
	v_pk_mul_f32 v[112:113], v[112:113], v[114:115] op_sel_hi:[1,0]
	v_pk_mul_f32 v[110:111], v[110:111], v[114:115] op_sel_hi:[1,0]
	v_pk_mul_f32 v[108:109], v[108:109], v[114:115] op_sel_hi:[1,0]
	v_pk_mul_f32 v[106:107], v[106:107], v[114:115] op_sel_hi:[1,0]
	s_and_saveexec_b64 s[6:7], s[8:9]
	s_cbranch_execz .LBB0_704
	v_mov_b32_e32 v115, s31
	v_cmp_gt_u32_e32 vcc, s72, v175
	s_nop 1
	v_cndmask_b32_e32 v115, v166, v115, vcc
	v_lshl_or_b32 v116, v115, 5, v176
	v_ashrrev_i32_e32 v117, 31, v116
	v_lshl_add_u64 v[120:121], v[116:117], 2, s[18:19]
	global_load_dwordx4 v[116:119], v[120:121], off
	global_load_dwordx4 v[154:157], v[120:121], off offset:16
	s_waitcnt vmcnt(1)
	v_pk_mul_f32 v[124:125], v[110:111], v[116:117] op_sel:[1,1] op_sel_hi:[1,0]
	v_mul_f32_e32 v128, v113, v119
	v_mul_f32_e32 v178, v113, v118
	s_waitcnt vmcnt(0)
	v_pk_mul_f32 v[182:183], v[106:107], v[154:155] op_sel:[1,1] op_sel_hi:[1,0]
	v_mul_f32_e32 v184, v109, v157
	v_mul_f32_e32 v186, v109, v156
	v_pk_mul_f32 v[120:121], v[110:111], v[116:117]
	v_pk_mul_f32 v[180:181], v[106:107], v[154:155]
	v_pk_fma_f32 v[110:111], v[110:111], v[116:117], v[124:125] op_sel_hi:[0,1,1]
	v_pk_fma_f32 v[116:117], v[112:113], v[118:119], v[128:129] op_sel_hi:[1,1,0] neg_lo:[0,0,1] neg_hi:[0,0,1]
	v_pk_fma_f32 v[118:119], v[112:113], v[118:119], v[178:179] op_sel:[0,1,0] op_sel_hi:[1,0,0]
	v_pk_fma_f32 v[106:107], v[106:107], v[154:155], v[182:183] op_sel_hi:[0,1,1]
	v_pk_fma_f32 v[112:113], v[108:109], v[156:157], v[184:185] op_sel_hi:[1,1,0] neg_lo:[0,0,1] neg_hi:[0,0,1]
	v_pk_fma_f32 v[128:129], v[108:109], v[156:157], v[186:187] op_sel:[0,1,0] op_sel_hi:[1,0,0]
	v_sub_f32_e32 v106, v180, v182
	v_sub_f32_e32 v110, v120, v124
	v_mov_b32_e32 v108, v112
	v_mov_b32_e32 v109, v128
	v_mov_b32_e32 v112, v116
	v_mov_b32_e32 v113, v118
.LBB0_704:
	s_or_b64 exec, exec, s[6:7]
	v_cvt_pk_bf16_f32 v110, v110, v111
	v_cvt_pk_bf16_f32 v111, v112, v113
	v_cvt_pk_bf16_f32 v112, v106, v107
	v_lshl_add_u64 v[106:107], v[122:123], 0, s[26:27]
	v_cvt_pk_bf16_f32 v113, v108, v109
	v_lshl_add_u64 v[108:109], v[148:149], 1, v[106:107]
	v_mov_b32_e32 v115, v114
	global_store_dwordx4 v[108:109], v[110:113], off nt
	v_pk_mul_f32 v[102:103], v[102:103], v[114:115]
	v_pk_mul_f32 v[98:99], v[98:99], v[114:115]
	v_mov_b32_e32 v110, v114
	v_mov_b32_e32 v111, v114
	v_pk_mul_f32 v[104:105], v[104:105], v[110:111]
	v_pk_mul_f32 v[100:101], v[100:101], v[110:111]
	s_and_saveexec_b64 s[6:7], s[42:43]
	s_cbranch_execz .LBB0_706
	v_mov_b32_e32 v110, s31
	v_cmp_gt_u32_e32 vcc, s72, v126
	s_nop 1
	v_cndmask_b32_e32 v110, v166, v110, vcc
	v_lshl_or_b32 v110, v110, 5, v127
	v_ashrrev_i32_e32 v111, 31, v110
	v_lshl_add_u64 v[114:115], v[110:111], 2, s[18:19]
	global_load_dwordx4 v[110:113], v[114:115], off
	s_nop 0
	global_load_dwordx4 v[114:117], v[114:115], off offset:16
	s_waitcnt vmcnt(1)
	v_pk_mul_f32 v[120:121], v[102:103], v[110:111] op_sel:[1,1] op_sel_hi:[1,0]
	v_mul_f32_e32 v122, v105, v113
	v_mul_f32_e32 v124, v105, v112
	s_waitcnt vmcnt(0)
	v_pk_mul_f32 v[154:155], v[98:99], v[114:115] op_sel:[1,1] op_sel_hi:[1,0]
	v_mul_f32_e32 v156, v101, v117
	v_mul_f32_e32 v178, v101, v116
	v_pk_mul_f32 v[118:119], v[102:103], v[110:111]
	v_pk_mul_f32 v[128:129], v[98:99], v[114:115]
	v_pk_fma_f32 v[102:103], v[102:103], v[110:111], v[120:121] op_sel_hi:[0,1,1]
	v_pk_fma_f32 v[110:111], v[104:105], v[112:113], v[122:123] op_sel_hi:[1,1,0] neg_lo:[0,0,1] neg_hi:[0,0,1]
	v_pk_fma_f32 v[112:113], v[104:105], v[112:113], v[124:125] op_sel:[0,1,0] op_sel_hi:[1,0,0]
	v_pk_fma_f32 v[98:99], v[98:99], v[114:115], v[154:155] op_sel_hi:[0,1,1]
	v_pk_fma_f32 v[104:105], v[100:101], v[116:117], v[156:157] op_sel_hi:[1,1,0] neg_lo:[0,0,1] neg_hi:[0,0,1]
	v_pk_fma_f32 v[114:115], v[100:101], v[116:117], v[178:179] op_sel:[0,1,0] op_sel_hi:[1,0,0]
	v_sub_f32_e32 v98, v128, v154
	v_sub_f32_e32 v102, v118, v120
	v_mov_b32_e32 v100, v104
	v_mov_b32_e32 v101, v114
	v_mov_b32_e32 v104, v110
	v_mov_b32_e32 v105, v112
.LBB0_706:
	s_or_b64 exec, exec, s[6:7]
	v_cvt_pk_bf16_f32 v102, v102, v103
	v_cvt_pk_bf16_f32 v103, v104, v105
	v_cvt_pk_bf16_f32 v104, v98, v99
	v_or_b32_e32 v98, 0x400, v152
	v_mov_b32_e32 v99, v153
	v_cvt_pk_bf16_f32 v105, v100, v101
	global_store_dwordx4 v[108:109], v[102:105], off offset:256 nt
	v_lshl_add_u64 v[98:99], s[12:13], 0, v[98:99]
	global_load_dwordx4 v[98:101], v[98:99], off
	s_waitcnt vmcnt(0)
	v_mov_b32_e32 v102, v99
	v_mov_b32_e32 v103, v100
	v_mov_b32_e32 v99, v101
	v_pk_add_f32 v[98:99], v[102:103], v[98:99]
	s_nop 0
	v_add_f32_e32 v98, v98, v99
	v_fmamk_f32 v98, v98, 0x3a800000, v173
	v_mul_f32_e32 v99, 0x4f800000, v98
	v_cmp_gt_f32_e32 vcc, s69, v98
	s_nop 1
	v_cndmask_b32_e32 v98, v98, v99, vcc
	v_sqrt_f32_e32 v99, v98
	s_nop 0
	v_add_u32_e32 v100, -1, v99
	v_add_u32_e32 v101, 1, v99
	v_fma_f32 v102, -v100, v99, v98
	v_fma_f32 v103, -v101, v99, v98
	v_cmp_ge_f32_e64 s[6:7], 0, v102
	s_nop 1
	v_cndmask_b32_e64 v99, v99, v100, s[6:7]
	v_cmp_lt_f32_e64 s[6:7], 0, v103
	s_nop 1
	v_cndmask_b32_e64 v99, v99, v101, s[6:7]
	v_mul_f32_e32 v100, 0x37800000, v99
	v_cndmask_b32_e32 v99, v99, v100, vcc
	v_cmp_class_f32_e32 vcc, v98, v174
	s_nop 1
	v_cndmask_b32_e32 v98, v99, v98, vcc
	v_div_scale_f32 v99, s[6:7], v98, v98, 1.0
	v_rcp_f32_e32 v100, v99
	v_div_scale_f32 v101, vcc, 1.0, v98, 1.0
	v_fma_f32 v102, -v99, v100, 1.0
	v_fmac_f32_e32 v100, v102, v100
	v_mul_f32_e32 v102, v101, v100
	v_fma_f32 v103, -v99, v102, v101
	v_fmac_f32_e32 v102, v103, v100
	v_fma_f32 v99, -v99, v102, v101
	v_div_fmas_f32 v99, v99, v100, v102
	v_div_fixup_f32 v98, v99, v98, 1.0
	v_pk_mul_f32 v[96:97], v[96:97], v[98:99] op_sel_hi:[1,0]
	v_pk_mul_f32 v[94:95], v[94:95], v[98:99] op_sel_hi:[1,0]
	v_pk_mul_f32 v[92:93], v[92:93], v[98:99] op_sel_hi:[1,0]
	v_pk_mul_f32 v[90:91], v[90:91], v[98:99] op_sel_hi:[1,0]
	s_and_saveexec_b64 s[6:7], s[8:9]
	s_cbranch_execz .LBB0_708
	v_mov_b32_e32 v99, s31
	v_cmp_gt_u32_e32 vcc, s72, v175
	s_nop 1
	v_cndmask_b32_e32 v99, v167, v99, vcc
	v_lshl_or_b32 v100, v99, 5, v176
	v_ashrrev_i32_e32 v101, 31, v100
	v_lshl_add_u64 v[104:105], v[100:101], 2, s[18:19]
	global_load_dwordx4 v[100:103], v[104:105], off
	global_load_dwordx4 v[108:111], v[104:105], off offset:16
	s_waitcnt vmcnt(1)
	v_pk_mul_f32 v[112:113], v[94:95], v[100:101] op_sel:[1,1] op_sel_hi:[1,0]
	v_mul_f32_e32 v114, v97, v103
	v_mul_f32_e32 v116, v97, v102
	s_waitcnt vmcnt(0)
	v_pk_mul_f32 v[120:121], v[90:91], v[108:109] op_sel:[1,1] op_sel_hi:[1,0]
	v_mul_f32_e32 v122, v93, v111
	v_mul_f32_e32 v124, v93, v110
	v_pk_mul_f32 v[104:105], v[94:95], v[100:101]
	v_pk_mul_f32 v[118:119], v[90:91], v[108:109]
	v_pk_fma_f32 v[94:95], v[94:95], v[100:101], v[112:113] op_sel_hi:[0,1,1]
	v_pk_fma_f32 v[100:101], v[96:97], v[102:103], v[114:115] op_sel_hi:[1,1,0] neg_lo:[0,0,1] neg_hi:[0,0,1]
	v_pk_fma_f32 v[102:103], v[96:97], v[102:103], v[116:117] op_sel:[0,1,0] op_sel_hi:[1,0,0]
	v_pk_fma_f32 v[90:91], v[90:91], v[108:109], v[120:121] op_sel_hi:[0,1,1]
	v_pk_fma_f32 v[96:97], v[92:93], v[110:111], v[122:123] op_sel_hi:[1,1,0] neg_lo:[0,0,1] neg_hi:[0,0,1]
	v_pk_fma_f32 v[108:109], v[92:93], v[110:111], v[124:125] op_sel:[0,1,0] op_sel_hi:[1,0,0]
	v_sub_f32_e32 v90, v118, v120
	v_sub_f32_e32 v94, v104, v112
	v_mov_b32_e32 v92, v96
	v_mov_b32_e32 v93, v108
	v_mov_b32_e32 v96, v100
	v_mov_b32_e32 v97, v102
.LBB0_708:
	s_or_b64 exec, exec, s[6:7]
	v_cvt_pk_bf16_f32 v94, v94, v95
	v_cvt_pk_bf16_f32 v95, v96, v97
	v_cvt_pk_bf16_f32 v96, v90, v91
	v_lshl_add_u64 v[90:91], v[106:107], 0, s[26:27]
	v_cvt_pk_bf16_f32 v97, v92, v93
	v_lshl_add_u64 v[92:93], v[148:149], 1, v[90:91]
	v_mov_b32_e32 v99, v98
	global_store_dwordx4 v[92:93], v[94:97], off nt
	v_pk_mul_f32 v[86:87], v[86:87], v[98:99]
	v_pk_mul_f32 v[82:83], v[82:83], v[98:99]
	v_mov_b32_e32 v94, v98
	v_mov_b32_e32 v95, v98
	v_pk_mul_f32 v[88:89], v[88:89], v[94:95]
	v_pk_mul_f32 v[84:85], v[84:85], v[94:95]
	s_and_saveexec_b64 s[6:7], s[42:43]
	s_cbranch_execz .LBB0_710
	v_mov_b32_e32 v94, s31
	v_cmp_gt_u32_e32 vcc, s72, v126
	s_nop 1
	v_cndmask_b32_e32 v94, v167, v94, vcc
	v_lshl_or_b32 v94, v94, 5, v127
	v_ashrrev_i32_e32 v95, 31, v94
	v_lshl_add_u64 v[98:99], v[94:95], 2, s[18:19]
	global_load_dwordx4 v[94:97], v[98:99], off
	s_nop 0
	global_load_dwordx4 v[98:101], v[98:99], off offset:16
	s_waitcnt vmcnt(1)
	v_pk_mul_f32 v[104:105], v[86:87], v[94:95] op_sel:[1,1] op_sel_hi:[1,0]
	v_mul_f32_e32 v106, v89, v97
	v_mul_f32_e32 v108, v89, v96
	s_waitcnt vmcnt(0)
	v_pk_mul_f32 v[112:113], v[82:83], v[98:99] op_sel:[1,1] op_sel_hi:[1,0]
	v_mul_f32_e32 v114, v85, v101
	v_mul_f32_e32 v116, v85, v100
	v_pk_mul_f32 v[102:103], v[86:87], v[94:95]
	v_pk_mul_f32 v[110:111], v[82:83], v[98:99]
	v_pk_fma_f32 v[86:87], v[86:87], v[94:95], v[104:105] op_sel_hi:[0,1,1]
	v_pk_fma_f32 v[94:95], v[88:89], v[96:97], v[106:107] op_sel_hi:[1,1,0] neg_lo:[0,0,1] neg_hi:[0,0,1]
	v_pk_fma_f32 v[96:97], v[88:89], v[96:97], v[108:109] op_sel:[0,1,0] op_sel_hi:[1,0,0]
	v_pk_fma_f32 v[82:83], v[82:83], v[98:99], v[112:113] op_sel_hi:[0,1,1]
	v_pk_fma_f32 v[88:89], v[84:85], v[100:101], v[114:115] op_sel_hi:[1,1,0] neg_lo:[0,0,1] neg_hi:[0,0,1]
	v_pk_fma_f32 v[98:99], v[84:85], v[100:101], v[116:117] op_sel:[0,1,0] op_sel_hi:[1,0,0]
	v_sub_f32_e32 v82, v110, v112
	v_sub_f32_e32 v86, v102, v104
	v_mov_b32_e32 v84, v88
	v_mov_b32_e32 v85, v98
	v_mov_b32_e32 v88, v94
	v_mov_b32_e32 v89, v96
.LBB0_710:
	s_or_b64 exec, exec, s[6:7]
	v_or_b32_e32 v152, 0x600, v152
	v_cvt_pk_bf16_f32 v86, v86, v87
	v_cvt_pk_bf16_f32 v87, v88, v89
	v_cvt_pk_bf16_f32 v88, v82, v83
	v_cvt_pk_bf16_f32 v89, v84, v85
	global_store_dwordx4 v[92:93], v[86:89], off offset:256 nt
	v_lshl_add_u64 v[82:83], s[12:13], 0, v[152:153]
	global_load_dwordx4 v[82:85], v[82:83], off
	s_waitcnt vmcnt(0)
	v_mov_b32_e32 v86, v83
	v_mov_b32_e32 v87, v84
	v_mov_b32_e32 v83, v85
	v_pk_add_f32 v[82:83], v[86:87], v[82:83]
	s_nop 0
	v_add_f32_e32 v82, v82, v83
	v_fmamk_f32 v82, v82, 0x3a800000, v173
	v_mul_f32_e32 v83, 0x4f800000, v82
	v_cmp_gt_f32_e32 vcc, s69, v82
	s_nop 1
	v_cndmask_b32_e32 v82, v82, v83, vcc
	v_sqrt_f32_e32 v83, v82
	s_nop 0
	v_add_u32_e32 v84, -1, v83
	v_add_u32_e32 v85, 1, v83
	v_fma_f32 v86, -v84, v83, v82
	v_fma_f32 v87, -v85, v83, v82
	v_cmp_ge_f32_e64 s[6:7], 0, v86
	s_nop 1
	v_cndmask_b32_e64 v83, v83, v84, s[6:7]
	v_cmp_lt_f32_e64 s[6:7], 0, v87
	s_nop 1
	v_cndmask_b32_e64 v83, v83, v85, s[6:7]
	v_mul_f32_e32 v84, 0x37800000, v83
	v_cndmask_b32_e32 v83, v83, v84, vcc
	v_cmp_class_f32_e32 vcc, v82, v174
	s_nop 1
	v_cndmask_b32_e32 v82, v83, v82, vcc
	v_div_scale_f32 v83, s[6:7], v82, v82, 1.0
	v_rcp_f32_e32 v84, v83
	v_div_scale_f32 v85, vcc, 1.0, v82, 1.0
	v_fma_f32 v86, -v83, v84, 1.0
	v_fmac_f32_e32 v84, v86, v84
	v_mul_f32_e32 v86, v85, v84
	v_fma_f32 v87, -v83, v86, v85
	v_fmac_f32_e32 v86, v87, v84
	v_fma_f32 v83, -v83, v86, v85
	v_div_fmas_f32 v83, v83, v84, v86
	v_div_fixup_f32 v82, v83, v82, 1.0
	v_pk_mul_f32 v[80:81], v[80:81], v[82:83] op_sel_hi:[1,0]
	v_pk_mul_f32 v[78:79], v[78:79], v[82:83] op_sel_hi:[1,0]
	v_pk_mul_f32 v[76:77], v[76:77], v[82:83] op_sel_hi:[1,0]
	v_pk_mul_f32 v[74:75], v[74:75], v[82:83] op_sel_hi:[1,0]
	s_and_saveexec_b64 s[6:7], s[8:9]
	s_cbranch_execz .LBB0_712
	v_mov_b32_e32 v83, s31
	v_cmp_gt_u32_e32 vcc, s72, v175
	s_nop 1
	v_cndmask_b32_e32 v83, v168, v83, vcc
	v_lshl_or_b32 v84, v83, 5, v176
	v_ashrrev_i32_e32 v85, 31, v84
	v_lshl_add_u64 v[88:89], v[84:85], 2, s[18:19]
	global_load_dwordx4 v[84:87], v[88:89], off
	global_load_dwordx4 v[92:95], v[88:89], off offset:16
	s_waitcnt vmcnt(1)
	v_pk_mul_f32 v[96:97], v[78:79], v[84:85] op_sel:[1,1] op_sel_hi:[1,0]
	v_mul_f32_e32 v98, v81, v87
	v_mul_f32_e32 v100, v81, v86
	s_waitcnt vmcnt(0)
	v_pk_mul_f32 v[104:105], v[74:75], v[92:93] op_sel:[1,1] op_sel_hi:[1,0]
	v_mul_f32_e32 v106, v77, v95
	v_mul_f32_e32 v108, v77, v94
	v_pk_mul_f32 v[88:89], v[78:79], v[84:85]
	v_pk_mul_f32 v[102:103], v[74:75], v[92:93]
	v_pk_fma_f32 v[78:79], v[78:79], v[84:85], v[96:97] op_sel_hi:[0,1,1]
	v_pk_fma_f32 v[84:85], v[80:81], v[86:87], v[98:99] op_sel_hi:[1,1,0] neg_lo:[0,0,1] neg_hi:[0,0,1]
	v_pk_fma_f32 v[86:87], v[80:81], v[86:87], v[100:101] op_sel:[0,1,0] op_sel_hi:[1,0,0]
	v_pk_fma_f32 v[74:75], v[74:75], v[92:93], v[104:105] op_sel_hi:[0,1,1]
	v_pk_fma_f32 v[80:81], v[76:77], v[94:95], v[106:107] op_sel_hi:[1,1,0] neg_lo:[0,0,1] neg_hi:[0,0,1]
	v_pk_fma_f32 v[92:93], v[76:77], v[94:95], v[108:109] op_sel:[0,1,0] op_sel_hi:[1,0,0]
	v_sub_f32_e32 v74, v102, v104
	v_sub_f32_e32 v78, v88, v96
	v_mov_b32_e32 v76, v80
	v_mov_b32_e32 v77, v92
	v_mov_b32_e32 v80, v84
	v_mov_b32_e32 v81, v86
.LBB0_712:
	s_or_b64 exec, exec, s[6:7]
	v_cvt_pk_bf16_f32 v78, v78, v79
	v_cvt_pk_bf16_f32 v79, v80, v81
	v_cvt_pk_bf16_f32 v80, v74, v75
	v_lshl_add_u64 v[74:75], v[90:91], 0, s[26:27]
	v_cvt_pk_bf16_f32 v81, v76, v77
	v_lshl_add_u64 v[76:77], v[148:149], 1, v[74:75]
	v_mov_b32_e32 v83, v82
	global_store_dwordx4 v[76:77], v[78:81], off nt
	v_pk_mul_f32 v[70:71], v[70:71], v[82:83]
	v_pk_mul_f32 v[66:67], v[66:67], v[82:83]
	v_mov_b32_e32 v78, v82
	v_mov_b32_e32 v79, v82
	v_pk_mul_f32 v[72:73], v[72:73], v[78:79]
	v_pk_mul_f32 v[68:69], v[68:69], v[78:79]
	s_and_saveexec_b64 s[6:7], s[42:43]
	s_cbranch_execz .LBB0_714
	v_mov_b32_e32 v78, s31
	v_cmp_gt_u32_e32 vcc, s72, v126
	s_nop 1
	v_cndmask_b32_e32 v78, v168, v78, vcc
	v_lshl_or_b32 v78, v78, 5, v127
	v_ashrrev_i32_e32 v79, 31, v78
	v_lshl_add_u64 v[82:83], v[78:79], 2, s[18:19]
	global_load_dwordx4 v[78:81], v[82:83], off
	s_nop 0
	global_load_dwordx4 v[82:85], v[82:83], off offset:16
	s_waitcnt vmcnt(1)
	v_pk_mul_f32 v[88:89], v[70:71], v[78:79] op_sel:[1,1] op_sel_hi:[1,0]
	v_mul_f32_e32 v90, v73, v81
	v_mul_f32_e32 v92, v73, v80
	s_waitcnt vmcnt(0)
	v_pk_mul_f32 v[96:97], v[66:67], v[82:83] op_sel:[1,1] op_sel_hi:[1,0]
	v_mul_f32_e32 v98, v69, v85
	v_mul_f32_e32 v100, v69, v84
	v_pk_mul_f32 v[86:87], v[70:71], v[78:79]
	v_pk_mul_f32 v[94:95], v[66:67], v[82:83]
	v_pk_fma_f32 v[70:71], v[70:71], v[78:79], v[88:89] op_sel_hi:[0,1,1]
	v_pk_fma_f32 v[78:79], v[72:73], v[80:81], v[90:91] op_sel_hi:[1,1,0] neg_lo:[0,0,1] neg_hi:[0,0,1]
	v_pk_fma_f32 v[80:81], v[72:73], v[80:81], v[92:93] op_sel:[0,1,0] op_sel_hi:[1,0,0]
	v_pk_fma_f32 v[66:67], v[66:67], v[82:83], v[96:97] op_sel_hi:[0,1,1]
	v_pk_fma_f32 v[72:73], v[68:69], v[84:85], v[98:99] op_sel_hi:[1,1,0] neg_lo:[0,0,1] neg_hi:[0,0,1]
	v_pk_fma_f32 v[82:83], v[68:69], v[84:85], v[100:101] op_sel:[0,1,0] op_sel_hi:[1,0,0]
	v_sub_f32_e32 v66, v94, v96
	v_sub_f32_e32 v70, v86, v88
	v_mov_b32_e32 v68, v72
	v_mov_b32_e32 v69, v82
	v_mov_b32_e32 v72, v78
	v_mov_b32_e32 v73, v80
.LBB0_714:
	s_or_b64 exec, exec, s[6:7]
	v_cvt_pk_bf16_f32 v70, v70, v71
	v_cvt_pk_bf16_f32 v71, v72, v73
	v_cvt_pk_bf16_f32 v72, v66, v67
	v_add_co_u32_e32 v66, vcc, s74, v150
	v_cvt_pk_bf16_f32 v73, v68, v69
	global_store_dwordx4 v[76:77], v[70:73], off offset:256 nt
	s_nop 0
	v_addc_co_u32_e32 v67, vcc, 0, v151, vcc
	global_load_dwordx4 v[68:71], v[66:67], off
	s_add_i32 s31, s31, 2
	s_waitcnt vmcnt(0)
	v_mov_b32_e32 v72, v69
	v_mov_b32_e32 v73, v70
	v_mov_b32_e32 v69, v71
	v_pk_add_f32 v[68:69], v[72:73], v[68:69]
	s_nop 0
	v_add_f32_e32 v68, v68, v69
	v_fmamk_f32 v68, v68, 0x3a800000, v173
	v_mul_f32_e32 v69, 0x4f800000, v68
	v_cmp_gt_f32_e32 vcc, s69, v68
	s_nop 1
	v_cndmask_b32_e32 v68, v68, v69, vcc
	v_sqrt_f32_e32 v69, v68
	s_nop 0
	v_add_u32_e32 v70, -1, v69
	v_add_u32_e32 v71, 1, v69
	v_fma_f32 v72, -v70, v69, v68
	v_fma_f32 v73, -v71, v69, v68
	v_cmp_ge_f32_e64 s[6:7], 0, v72
	s_nop 1
	v_cndmask_b32_e64 v69, v69, v70, s[6:7]
	v_cmp_lt_f32_e64 s[6:7], 0, v73
	s_nop 1
	v_cndmask_b32_e64 v69, v69, v71, s[6:7]
	v_mul_f32_e32 v70, 0x37800000, v69
	v_cndmask_b32_e32 v69, v69, v70, vcc
	v_cmp_class_f32_e32 vcc, v68, v174
	s_nop 1
	v_cndmask_b32_e32 v68, v69, v68, vcc
	v_div_scale_f32 v69, s[6:7], v68, v68, 1.0
	v_rcp_f32_e32 v70, v69
	v_div_scale_f32 v71, vcc, 1.0, v68, 1.0
	v_fma_f32 v72, -v69, v70, 1.0
	v_fmac_f32_e32 v70, v72, v70
	v_mul_f32_e32 v72, v71, v70
	v_fma_f32 v73, -v69, v72, v71
	v_fmac_f32_e32 v72, v73, v70
	v_fma_f32 v69, -v69, v72, v71
	v_div_fmas_f32 v69, v69, v70, v72
	v_div_fixup_f32 v68, v69, v68, 1.0
	v_pk_mul_f32 v[64:65], v[64:65], v[68:69] op_sel_hi:[1,0]
	v_pk_mul_f32 v[62:63], v[62:63], v[68:69] op_sel_hi:[1,0]
	v_pk_mul_f32 v[60:61], v[60:61], v[68:69] op_sel_hi:[1,0]
	v_pk_mul_f32 v[58:59], v[58:59], v[68:69] op_sel_hi:[1,0]
	s_and_saveexec_b64 s[6:7], s[8:9]
	s_cbranch_execz .LBB0_716
	v_mov_b32_e32 v69, s31
	v_cmp_gt_u32_e32 vcc, s72, v175
	s_nop 1
	v_cndmask_b32_e32 v69, v159, v69, vcc
	v_lshl_or_b32 v70, v69, 5, v176
	v_ashrrev_i32_e32 v71, 31, v70
	v_lshl_add_u64 v[76:77], v[70:71], 2, s[18:19]
	global_load_dwordx4 v[70:73], v[76:77], off
	s_nop 0
	global_load_dwordx4 v[76:79], v[76:77], off offset:16
	s_waitcnt vmcnt(1)
	v_pk_mul_f32 v[82:83], v[62:63], v[70:71] op_sel:[1,1] op_sel_hi:[1,0]
	v_mul_f32_e32 v84, v65, v73
	v_mul_f32_e32 v86, v65, v72
	s_waitcnt vmcnt(0)
	v_pk_mul_f32 v[90:91], v[58:59], v[76:77] op_sel:[1,1] op_sel_hi:[1,0]
	v_mul_f32_e32 v92, v61, v79
	v_mul_f32_e32 v94, v61, v78
	v_pk_mul_f32 v[80:81], v[62:63], v[70:71]
	v_pk_mul_f32 v[88:89], v[58:59], v[76:77]
	v_pk_fma_f32 v[62:63], v[62:63], v[70:71], v[82:83] op_sel_hi:[0,1,1]
	v_pk_fma_f32 v[70:71], v[64:65], v[72:73], v[84:85] op_sel_hi:[1,1,0] neg_lo:[0,0,1] neg_hi:[0,0,1]
	v_pk_fma_f32 v[72:73], v[64:65], v[72:73], v[86:87] op_sel:[0,1,0] op_sel_hi:[1,0,0]
	v_pk_fma_f32 v[58:59], v[58:59], v[76:77], v[90:91] op_sel_hi:[0,1,1]
	v_pk_fma_f32 v[64:65], v[60:61], v[78:79], v[92:93] op_sel_hi:[1,1,0] neg_lo:[0,0,1] neg_hi:[0,0,1]
	v_pk_fma_f32 v[76:77], v[60:61], v[78:79], v[94:95] op_sel:[0,1,0] op_sel_hi:[1,0,0]
	v_sub_f32_e32 v58, v88, v90
	v_sub_f32_e32 v62, v80, v82
	v_mov_b32_e32 v60, v64
	v_mov_b32_e32 v61, v76
	v_mov_b32_e32 v64, v70
	v_mov_b32_e32 v65, v72
.LBB0_716:
	s_or_b64 exec, exec, s[6:7]
	v_cvt_pk_bf16_f32 v62, v62, v63
	v_cvt_pk_bf16_f32 v63, v64, v65
	v_cvt_pk_bf16_f32 v64, v58, v59
	v_lshl_add_u64 v[58:59], v[74:75], 0, s[28:29]
	v_cvt_pk_bf16_f32 v65, v60, v61
	v_lshl_add_u64 v[60:61], v[148:149], 1, v[58:59]
	v_mov_b32_e32 v69, v68
	global_store_dwordx4 v[60:61], v[62:65], off nt
	v_pk_mul_f32 v[54:55], v[54:55], v[68:69]
	v_pk_mul_f32 v[50:51], v[50:51], v[68:69]
	v_mov_b32_e32 v62, v68
	v_mov_b32_e32 v63, v68
	v_pk_mul_f32 v[56:57], v[56:57], v[62:63]
	v_pk_mul_f32 v[52:53], v[52:53], v[62:63]
	s_and_saveexec_b64 s[6:7], s[42:43]
	s_cbranch_execz .LBB0_718
	v_mov_b32_e32 v62, s31
	v_cmp_gt_u32_e32 vcc, s72, v126
	s_nop 1
	v_cndmask_b32_e32 v62, v159, v62, vcc
	v_lshl_or_b32 v62, v62, 5, v127
	v_ashrrev_i32_e32 v63, 31, v62
	v_lshl_add_u64 v[68:69], v[62:63], 2, s[18:19]
	global_load_dwordx4 v[62:65], v[68:69], off
	s_nop 0
	global_load_dwordx4 v[68:71], v[68:69], off offset:16
	s_waitcnt vmcnt(1)
	v_pk_mul_f32 v[74:75], v[54:55], v[62:63] op_sel:[1,1] op_sel_hi:[1,0]
	v_mul_f32_e32 v76, v57, v65
	v_mul_f32_e32 v78, v57, v64
	s_waitcnt vmcnt(0)
	v_pk_mul_f32 v[82:83], v[50:51], v[68:69] op_sel:[1,1] op_sel_hi:[1,0]
	v_mul_f32_e32 v84, v53, v71
	v_mul_f32_e32 v86, v53, v70
	v_pk_mul_f32 v[72:73], v[54:55], v[62:63]
	v_pk_mul_f32 v[80:81], v[50:51], v[68:69]
	v_pk_fma_f32 v[54:55], v[54:55], v[62:63], v[74:75] op_sel_hi:[0,1,1]
	v_pk_fma_f32 v[62:63], v[56:57], v[64:65], v[76:77] op_sel_hi:[1,1,0] neg_lo:[0,0,1] neg_hi:[0,0,1]
	v_pk_fma_f32 v[64:65], v[56:57], v[64:65], v[78:79] op_sel:[0,1,0] op_sel_hi:[1,0,0]
	v_pk_fma_f32 v[50:51], v[50:51], v[68:69], v[82:83] op_sel_hi:[0,1,1]
	v_pk_fma_f32 v[56:57], v[52:53], v[70:71], v[84:85] op_sel_hi:[1,1,0] neg_lo:[0,0,1] neg_hi:[0,0,1]
	v_pk_fma_f32 v[68:69], v[52:53], v[70:71], v[86:87] op_sel:[0,1,0] op_sel_hi:[1,0,0]
	v_sub_f32_e32 v50, v80, v82
	v_sub_f32_e32 v54, v72, v74
	v_mov_b32_e32 v52, v56
	v_mov_b32_e32 v53, v68
	v_mov_b32_e32 v56, v62
	v_mov_b32_e32 v57, v64
.LBB0_718:
	s_or_b64 exec, exec, s[6:7]
	v_cvt_pk_bf16_f32 v54, v54, v55
	v_cvt_pk_bf16_f32 v55, v56, v57
	v_cvt_pk_bf16_f32 v56, v50, v51
	v_cvt_pk_bf16_f32 v57, v52, v53
	global_store_dwordx4 v[60:61], v[54:57], off offset:256 nt
	global_load_dwordx4 v[50:53], v[66:67], off offset:512
	s_waitcnt vmcnt(0)
	v_mov_b32_e32 v54, v51
	v_mov_b32_e32 v55, v52
	v_mov_b32_e32 v51, v53
	v_pk_add_f32 v[50:51], v[54:55], v[50:51]
	s_nop 0
	v_add_f32_e32 v50, v50, v51
	v_fmamk_f32 v50, v50, 0x3a800000, v173
	v_mul_f32_e32 v51, 0x4f800000, v50
	v_cmp_gt_f32_e32 vcc, s69, v50
	s_nop 1
	v_cndmask_b32_e32 v50, v50, v51, vcc
	v_sqrt_f32_e32 v51, v50
	s_nop 0
	v_add_u32_e32 v52, -1, v51
	v_add_u32_e32 v53, 1, v51
	v_fma_f32 v54, -v52, v51, v50
	v_fma_f32 v55, -v53, v51, v50
	v_cmp_ge_f32_e64 s[6:7], 0, v54
	s_nop 1
	v_cndmask_b32_e64 v51, v51, v52, s[6:7]
	v_cmp_lt_f32_e64 s[6:7], 0, v55
	s_nop 1
	v_cndmask_b32_e64 v51, v51, v53, s[6:7]
	v_mul_f32_e32 v52, 0x37800000, v51
	v_cndmask_b32_e32 v51, v51, v52, vcc
	v_cmp_class_f32_e32 vcc, v50, v174
	s_nop 1
	v_cndmask_b32_e32 v50, v51, v50, vcc
	v_div_scale_f32 v51, s[6:7], v50, v50, 1.0
	v_rcp_f32_e32 v52, v51
	v_div_scale_f32 v53, vcc, 1.0, v50, 1.0
	v_fma_f32 v54, -v51, v52, 1.0
	v_fmac_f32_e32 v52, v54, v52
	v_mul_f32_e32 v54, v53, v52
	v_fma_f32 v55, -v51, v54, v53
	v_fmac_f32_e32 v54, v55, v52
	v_fma_f32 v51, -v51, v54, v53
	v_div_fmas_f32 v51, v51, v52, v54
	v_div_fixup_f32 v50, v51, v50, 1.0
	v_pk_mul_f32 v[48:49], v[48:49], v[50:51] op_sel_hi:[1,0]
	v_pk_mul_f32 v[46:47], v[46:47], v[50:51] op_sel_hi:[1,0]
	v_pk_mul_f32 v[44:45], v[44:45], v[50:51] op_sel_hi:[1,0]
	v_pk_mul_f32 v[42:43], v[42:43], v[50:51] op_sel_hi:[1,0]
	s_and_saveexec_b64 s[6:7], s[8:9]
	s_cbranch_execz .LBB0_720
	v_mov_b32_e32 v51, s31
	v_cmp_gt_u32_e32 vcc, s72, v175
	s_nop 1
	v_cndmask_b32_e32 v51, v166, v51, vcc
	v_lshl_or_b32 v52, v51, 5, v176
	v_ashrrev_i32_e32 v53, 31, v52
	v_lshl_add_u64 v[56:57], v[52:53], 2, s[18:19]
	global_load_dwordx4 v[52:55], v[56:57], off
	global_load_dwordx4 v[60:63], v[56:57], off offset:16
	s_waitcnt vmcnt(1)
	v_pk_mul_f32 v[64:65], v[46:47], v[52:53] op_sel:[1,1] op_sel_hi:[1,0]
	v_mul_f32_e32 v68, v49, v55
	v_mul_f32_e32 v70, v49, v54
	s_waitcnt vmcnt(0)
	v_pk_mul_f32 v[74:75], v[42:43], v[60:61] op_sel:[1,1] op_sel_hi:[1,0]
	v_mul_f32_e32 v76, v45, v63
	v_mul_f32_e32 v78, v45, v62
	v_pk_mul_f32 v[56:57], v[46:47], v[52:53]
	v_pk_mul_f32 v[72:73], v[42:43], v[60:61]
	v_pk_fma_f32 v[46:47], v[46:47], v[52:53], v[64:65] op_sel_hi:[0,1,1]
	v_pk_fma_f32 v[52:53], v[48:49], v[54:55], v[68:69] op_sel_hi:[1,1,0] neg_lo:[0,0,1] neg_hi:[0,0,1]
	v_pk_fma_f32 v[54:55], v[48:49], v[54:55], v[70:71] op_sel:[0,1,0] op_sel_hi:[1,0,0]
	v_pk_fma_f32 v[42:43], v[42:43], v[60:61], v[74:75] op_sel_hi:[0,1,1]
	v_pk_fma_f32 v[48:49], v[44:45], v[62:63], v[76:77] op_sel_hi:[1,1,0] neg_lo:[0,0,1] neg_hi:[0,0,1]
	v_pk_fma_f32 v[60:61], v[44:45], v[62:63], v[78:79] op_sel:[0,1,0] op_sel_hi:[1,0,0]
	v_sub_f32_e32 v42, v72, v74
	v_sub_f32_e32 v46, v56, v64
	v_mov_b32_e32 v44, v48
	v_mov_b32_e32 v45, v60
	v_mov_b32_e32 v48, v52
	v_mov_b32_e32 v49, v54
.LBB0_720:
	s_or_b64 exec, exec, s[6:7]
	v_cvt_pk_bf16_f32 v46, v46, v47
	v_cvt_pk_bf16_f32 v47, v48, v49
	v_cvt_pk_bf16_f32 v48, v42, v43
	v_lshl_add_u64 v[42:43], v[58:59], 0, s[26:27]
	v_cvt_pk_bf16_f32 v49, v44, v45
	v_lshl_add_u64 v[44:45], v[148:149], 1, v[42:43]
	v_mov_b32_e32 v51, v50
	global_store_dwordx4 v[44:45], v[46:49], off nt
	v_pk_mul_f32 v[38:39], v[38:39], v[50:51]
	v_pk_mul_f32 v[34:35], v[34:35], v[50:51]
	v_mov_b32_e32 v46, v50
	v_mov_b32_e32 v47, v50
	v_pk_mul_f32 v[40:41], v[40:41], v[46:47]
	v_pk_mul_f32 v[36:37], v[36:37], v[46:47]
	s_and_saveexec_b64 s[6:7], s[42:43]
	s_cbranch_execz .LBB0_722
	v_mov_b32_e32 v46, s31
	v_cmp_gt_u32_e32 vcc, s72, v126
	s_nop 1
	v_cndmask_b32_e32 v46, v166, v46, vcc
	v_lshl_or_b32 v46, v46, 5, v127
	v_ashrrev_i32_e32 v47, 31, v46
	v_lshl_add_u64 v[50:51], v[46:47], 2, s[18:19]
	global_load_dwordx4 v[46:49], v[50:51], off
	s_nop 0
	global_load_dwordx4 v[50:53], v[50:51], off offset:16
	s_waitcnt vmcnt(1)
	v_pk_mul_f32 v[56:57], v[38:39], v[46:47] op_sel:[1,1] op_sel_hi:[1,0]
	v_mul_f32_e32 v58, v41, v49
	v_mul_f32_e32 v60, v41, v48
	s_waitcnt vmcnt(0)
	v_pk_mul_f32 v[64:65], v[34:35], v[50:51] op_sel:[1,1] op_sel_hi:[1,0]
	v_mul_f32_e32 v68, v37, v53
	v_mul_f32_e32 v70, v37, v52
	v_pk_mul_f32 v[54:55], v[38:39], v[46:47]
	v_pk_mul_f32 v[62:63], v[34:35], v[50:51]
	v_pk_fma_f32 v[38:39], v[38:39], v[46:47], v[56:57] op_sel_hi:[0,1,1]
	v_pk_fma_f32 v[46:47], v[40:41], v[48:49], v[58:59] op_sel_hi:[1,1,0] neg_lo:[0,0,1] neg_hi:[0,0,1]
	v_pk_fma_f32 v[48:49], v[40:41], v[48:49], v[60:61] op_sel:[0,1,0] op_sel_hi:[1,0,0]
	v_pk_fma_f32 v[34:35], v[34:35], v[50:51], v[64:65] op_sel_hi:[0,1,1]
	v_pk_fma_f32 v[40:41], v[36:37], v[52:53], v[68:69] op_sel_hi:[1,1,0] neg_lo:[0,0,1] neg_hi:[0,0,1]
	v_pk_fma_f32 v[50:51], v[36:37], v[52:53], v[70:71] op_sel:[0,1,0] op_sel_hi:[1,0,0]
	v_sub_f32_e32 v34, v62, v64
	v_sub_f32_e32 v38, v54, v56
	v_mov_b32_e32 v36, v40
	v_mov_b32_e32 v37, v50
	v_mov_b32_e32 v40, v46
	v_mov_b32_e32 v41, v48
.LBB0_722:
	s_or_b64 exec, exec, s[6:7]
	v_cvt_pk_bf16_f32 v38, v38, v39
	v_cvt_pk_bf16_f32 v39, v40, v41
	v_cvt_pk_bf16_f32 v40, v34, v35
	v_cvt_pk_bf16_f32 v41, v36, v37
	global_store_dwordx4 v[44:45], v[38:41], off offset:256 nt
	global_load_dwordx4 v[34:37], v[66:67], off offset:1024
	s_waitcnt vmcnt(0)
	v_mov_b32_e32 v38, v35
	v_mov_b32_e32 v39, v36
	v_mov_b32_e32 v35, v37
	v_pk_add_f32 v[34:35], v[38:39], v[34:35]
	s_nop 0
	v_add_f32_e32 v34, v34, v35
	v_fmamk_f32 v34, v34, 0x3a800000, v173
	v_mul_f32_e32 v35, 0x4f800000, v34
	v_cmp_gt_f32_e32 vcc, s69, v34
	s_nop 1
	v_cndmask_b32_e32 v34, v34, v35, vcc
	v_sqrt_f32_e32 v35, v34
	s_nop 0
	v_add_u32_e32 v36, -1, v35
	v_add_u32_e32 v37, 1, v35
	v_fma_f32 v38, -v36, v35, v34
	v_fma_f32 v39, -v37, v35, v34
	v_cmp_ge_f32_e64 s[6:7], 0, v38
	s_nop 1
	v_cndmask_b32_e64 v35, v35, v36, s[6:7]
	v_cmp_lt_f32_e64 s[6:7], 0, v39
	s_nop 1
	v_cndmask_b32_e64 v35, v35, v37, s[6:7]
	v_mul_f32_e32 v36, 0x37800000, v35
	v_cndmask_b32_e32 v35, v35, v36, vcc
	v_cmp_class_f32_e32 vcc, v34, v174
	s_nop 1
	v_cndmask_b32_e32 v34, v35, v34, vcc
	v_div_scale_f32 v35, s[6:7], v34, v34, 1.0
	v_rcp_f32_e32 v36, v35
	v_div_scale_f32 v37, vcc, 1.0, v34, 1.0
	v_fma_f32 v38, -v35, v36, 1.0
	v_fmac_f32_e32 v36, v38, v36
	v_mul_f32_e32 v38, v37, v36
	v_fma_f32 v39, -v35, v38, v37
	v_fmac_f32_e32 v38, v39, v36
	v_fma_f32 v35, -v35, v38, v37
	v_div_fmas_f32 v35, v35, v36, v38
	v_div_fixup_f32 v34, v35, v34, 1.0
	v_pk_mul_f32 v[32:33], v[32:33], v[34:35] op_sel_hi:[1,0]
	v_pk_mul_f32 v[30:31], v[30:31], v[34:35] op_sel_hi:[1,0]
	v_pk_mul_f32 v[28:29], v[28:29], v[34:35] op_sel_hi:[1,0]
	v_pk_mul_f32 v[26:27], v[26:27], v[34:35] op_sel_hi:[1,0]
	s_and_saveexec_b64 s[6:7], s[8:9]
	s_cbranch_execz .LBB0_724
	v_mov_b32_e32 v35, s31
	v_cmp_gt_u32_e32 vcc, s72, v175
	s_nop 1
	v_cndmask_b32_e32 v35, v167, v35, vcc
	v_lshl_or_b32 v36, v35, 5, v176
	v_ashrrev_i32_e32 v37, 31, v36
	v_lshl_add_u64 v[40:41], v[36:37], 2, s[18:19]
	global_load_dwordx4 v[36:39], v[40:41], off
	global_load_dwordx4 v[44:47], v[40:41], off offset:16
	s_waitcnt vmcnt(1)
	v_pk_mul_f32 v[48:49], v[30:31], v[36:37] op_sel:[1,1] op_sel_hi:[1,0]
	v_mul_f32_e32 v50, v33, v39
	v_mul_f32_e32 v52, v33, v38
	s_waitcnt vmcnt(0)
	v_pk_mul_f32 v[56:57], v[26:27], v[44:45] op_sel:[1,1] op_sel_hi:[1,0]
	v_mul_f32_e32 v58, v29, v47
	v_mul_f32_e32 v60, v29, v46
	v_pk_mul_f32 v[40:41], v[30:31], v[36:37]
	v_pk_mul_f32 v[54:55], v[26:27], v[44:45]
	v_pk_fma_f32 v[30:31], v[30:31], v[36:37], v[48:49] op_sel_hi:[0,1,1]
	v_pk_fma_f32 v[36:37], v[32:33], v[38:39], v[50:51] op_sel_hi:[1,1,0] neg_lo:[0,0,1] neg_hi:[0,0,1]
	v_pk_fma_f32 v[38:39], v[32:33], v[38:39], v[52:53] op_sel:[0,1,0] op_sel_hi:[1,0,0]
	v_pk_fma_f32 v[26:27], v[26:27], v[44:45], v[56:57] op_sel_hi:[0,1,1]
	v_pk_fma_f32 v[32:33], v[28:29], v[46:47], v[58:59] op_sel_hi:[1,1,0] neg_lo:[0,0,1] neg_hi:[0,0,1]
	v_pk_fma_f32 v[44:45], v[28:29], v[46:47], v[60:61] op_sel:[0,1,0] op_sel_hi:[1,0,0]
	v_sub_f32_e32 v26, v54, v56
	v_sub_f32_e32 v30, v40, v48
	v_mov_b32_e32 v28, v32
	v_mov_b32_e32 v29, v44
	v_mov_b32_e32 v32, v36
	v_mov_b32_e32 v33, v38
.LBB0_724:
	s_or_b64 exec, exec, s[6:7]
	v_mov_b32_e32 v35, v34
	v_cvt_pk_bf16_f32 v30, v30, v31
	v_cvt_pk_bf16_f32 v31, v32, v33
	v_cvt_pk_bf16_f32 v32, v26, v27
	v_cvt_pk_bf16_f32 v33, v28, v29
	v_lshl_add_u64 v[26:27], v[42:43], 0, s[26:27]
	v_mov_b32_e32 v28, v34
	v_mov_b32_e32 v29, v34
	v_lshl_add_u64 v[26:27], v[148:149], 1, v[26:27]
	v_pk_mul_f32 v[24:25], v[24:25], v[28:29]
	v_pk_mul_f32 v[22:23], v[22:23], v[34:35]
	v_pk_mul_f32 v[20:21], v[20:21], v[28:29]
	v_pk_mul_f32 v[18:19], v[18:19], v[34:35]
	global_store_dwordx4 v[26:27], v[30:33], off nt
	s_and_saveexec_b64 s[6:7], s[42:43]
	s_cbranch_execz .LBB0_726
	v_mov_b32_e32 v28, s31
	v_cmp_gt_u32_e32 vcc, s72, v126
	s_nop 1
	v_cndmask_b32_e32 v28, v167, v28, vcc
	v_lshl_or_b32 v28, v28, 5, v127
	v_ashrrev_i32_e32 v29, 31, v28
	v_lshl_add_u64 v[32:33], v[28:29], 2, s[18:19]
	global_load_dwordx4 v[28:31], v[32:33], off
	s_nop 0
	global_load_dwordx4 v[32:35], v[32:33], off offset:16
	s_waitcnt vmcnt(1)
	v_pk_mul_f32 v[38:39], v[22:23], v[28:29] op_sel:[1,1] op_sel_hi:[1,0]
	v_mul_f32_e32 v40, v25, v31
	v_mul_f32_e32 v42, v25, v30
	s_waitcnt vmcnt(0)
	v_pk_mul_f32 v[46:47], v[18:19], v[32:33] op_sel:[1,1] op_sel_hi:[1,0]
	v_mul_f32_e32 v48, v21, v35
	v_mul_f32_e32 v50, v21, v34
	v_pk_mul_f32 v[36:37], v[22:23], v[28:29]
	v_pk_mul_f32 v[44:45], v[18:19], v[32:33]
	v_pk_fma_f32 v[22:23], v[22:23], v[28:29], v[38:39] op_sel_hi:[0,1,1]
	v_pk_fma_f32 v[28:29], v[24:25], v[30:31], v[40:41] op_sel_hi:[1,1,0] neg_lo:[0,0,1] neg_hi:[0,0,1]
	v_pk_fma_f32 v[30:31], v[24:25], v[30:31], v[42:43] op_sel:[0,1,0] op_sel_hi:[1,0,0]
	v_pk_fma_f32 v[18:19], v[18:19], v[32:33], v[46:47] op_sel_hi:[0,1,1]
	v_pk_fma_f32 v[24:25], v[20:21], v[34:35], v[48:49] op_sel_hi:[1,1,0] neg_lo:[0,0,1] neg_hi:[0,0,1]
	v_pk_fma_f32 v[32:33], v[20:21], v[34:35], v[50:51] op_sel:[0,1,0] op_sel_hi:[1,0,0]
	v_sub_f32_e32 v18, v44, v46
	v_sub_f32_e32 v22, v36, v38
	v_mov_b32_e32 v20, v24
	v_mov_b32_e32 v21, v32
	v_mov_b32_e32 v24, v28
	v_mov_b32_e32 v25, v30
.LBB0_726:
	s_or_b64 exec, exec, s[6:7]
	v_cvt_pk_bf16_f32 v22, v22, v23
	v_cvt_pk_bf16_f32 v23, v24, v25
	v_cvt_pk_bf16_f32 v24, v18, v19
	v_cvt_pk_bf16_f32 v25, v20, v21
	global_store_dwordx4 v[26:27], v[22:25], off offset:256 nt
	global_load_dwordx4 v[18:21], v[66:67], off offset:1536
	s_waitcnt vmcnt(0)
	v_mov_b32_e32 v22, v19
	v_mov_b32_e32 v23, v20
	v_mov_b32_e32 v19, v21
	v_pk_add_f32 v[18:19], v[22:23], v[18:19]
	s_nop 0
	v_add_f32_e32 v18, v18, v19
	v_fmamk_f32 v18, v18, 0x3a800000, v173
	v_mul_f32_e32 v19, 0x4f800000, v18
	v_cmp_gt_f32_e32 vcc, s69, v18
	s_nop 1
	v_cndmask_b32_e32 v18, v18, v19, vcc
	v_sqrt_f32_e32 v19, v18
	s_nop 0
	v_add_u32_e32 v20, -1, v19
	v_add_u32_e32 v21, 1, v19
	v_fma_f32 v22, -v20, v19, v18
	v_fma_f32 v23, -v21, v19, v18
	v_cmp_ge_f32_e64 s[6:7], 0, v22
	s_nop 1
	v_cndmask_b32_e64 v19, v19, v20, s[6:7]
	v_cmp_lt_f32_e64 s[6:7], 0, v23
	s_nop 1
	v_cndmask_b32_e64 v19, v19, v21, s[6:7]
	v_mul_f32_e32 v20, 0x37800000, v19
	v_cndmask_b32_e32 v19, v19, v20, vcc
	v_cmp_class_f32_e32 vcc, v18, v174
	s_nop 1
	v_cndmask_b32_e32 v18, v19, v18, vcc
	v_div_scale_f32 v19, s[6:7], v18, v18, 1.0
	v_rcp_f32_e32 v20, v19
	v_div_scale_f32 v21, vcc, 1.0, v18, 1.0
	v_fma_f32 v22, -v19, v20, 1.0
	v_fmac_f32_e32 v20, v22, v20
	v_mul_f32_e32 v22, v21, v20
	v_fma_f32 v23, -v19, v22, v21
	v_fmac_f32_e32 v22, v23, v20
	v_fma_f32 v19, -v19, v22, v21
	v_div_fmas_f32 v19, v19, v20, v22
	v_div_fixup_f32 v18, v19, v18, 1.0
	v_pk_mul_f32 v[16:17], v[16:17], v[18:19] op_sel_hi:[1,0]
	v_pk_mul_f32 v[14:15], v[14:15], v[18:19] op_sel_hi:[1,0]
	v_pk_mul_f32 v[12:13], v[12:13], v[18:19] op_sel_hi:[1,0]
	v_pk_mul_f32 v[10:11], v[10:11], v[18:19] op_sel_hi:[1,0]
	s_and_saveexec_b64 s[6:7], s[8:9]
	s_cbranch_execz .LBB0_728
	v_mov_b32_e32 v19, s31
	v_cmp_gt_u32_e32 vcc, s72, v175
	s_nop 1
	v_cndmask_b32_e32 v19, v168, v19, vcc
	v_lshl_or_b32 v20, v19, 5, v176
	v_ashrrev_i32_e32 v21, 31, v20
	v_lshl_add_u64 v[24:25], v[20:21], 2, s[18:19]
	global_load_dwordx4 v[20:23], v[24:25], off
	global_load_dwordx4 v[28:31], v[24:25], off offset:16
	s_waitcnt vmcnt(1)
	v_pk_mul_f32 v[32:33], v[14:15], v[20:21] op_sel:[1,1] op_sel_hi:[1,0]
	v_mul_f32_e32 v34, v17, v23
	v_mul_f32_e32 v36, v17, v22
	s_waitcnt vmcnt(0)
	v_pk_mul_f32 v[40:41], v[10:11], v[28:29] op_sel:[1,1] op_sel_hi:[1,0]
	v_mul_f32_e32 v42, v13, v31
	v_mul_f32_e32 v44, v13, v30
	v_pk_mul_f32 v[24:25], v[14:15], v[20:21]
	v_pk_mul_f32 v[38:39], v[10:11], v[28:29]
	v_pk_fma_f32 v[14:15], v[14:15], v[20:21], v[32:33] op_sel_hi:[0,1,1]
	v_pk_fma_f32 v[20:21], v[16:17], v[22:23], v[34:35] op_sel_hi:[1,1,0] neg_lo:[0,0,1] neg_hi:[0,0,1]
	v_pk_fma_f32 v[22:23], v[16:17], v[22:23], v[36:37] op_sel:[0,1,0] op_sel_hi:[1,0,0]
	v_pk_fma_f32 v[10:11], v[10:11], v[28:29], v[40:41] op_sel_hi:[0,1,1]
	v_pk_fma_f32 v[16:17], v[12:13], v[30:31], v[42:43] op_sel_hi:[1,1,0] neg_lo:[0,0,1] neg_hi:[0,0,1]
	v_pk_fma_f32 v[28:29], v[12:13], v[30:31], v[44:45] op_sel:[0,1,0] op_sel_hi:[1,0,0]
	v_sub_f32_e32 v10, v38, v40
	v_sub_f32_e32 v14, v24, v32
	v_mov_b32_e32 v12, v16
	v_mov_b32_e32 v13, v28
	v_mov_b32_e32 v16, v20
	v_mov_b32_e32 v17, v22
.LBB0_728:
	s_or_b64 exec, exec, s[6:7]
	v_cvt_pk_bf16_f32 v14, v14, v15
	v_cvt_pk_bf16_f32 v15, v16, v17
	v_cvt_pk_bf16_f32 v16, v10, v11
	v_add_co_u32_e32 v10, vcc, 0x18000, v26
	v_mov_b32_e32 v19, v18
	s_nop 0
	v_addc_co_u32_e32 v11, vcc, 0, v27, vcc
	v_cvt_pk_bf16_f32 v17, v12, v13
	global_store_dwordx4 v[10:11], v[14:17], off nt
	v_mov_b32_e32 v10, v18
	v_mov_b32_e32 v11, v18
	v_pk_mul_f32 v[8:9], v[8:9], v[10:11]
	v_pk_mul_f32 v[6:7], v[6:7], v[18:19]
	v_pk_mul_f32 v[4:5], v[4:5], v[10:11]
	v_pk_mul_f32 v[2:3], v[2:3], v[18:19]
	s_and_saveexec_b64 s[6:7], s[42:43]
	s_cbranch_execz .LBB0_730
	v_mov_b32_e32 v10, s31
	v_cmp_gt_u32_e32 vcc, s72, v126
	s_nop 1
	v_cndmask_b32_e32 v10, v168, v10, vcc
	v_lshl_or_b32 v10, v10, 5, v127
	v_ashrrev_i32_e32 v11, 31, v10
	v_lshl_add_u64 v[14:15], v[10:11], 2, s[18:19]
	global_load_dwordx4 v[10:13], v[14:15], off
	s_nop 0
	global_load_dwordx4 v[14:17], v[14:15], off offset:16
	s_waitcnt vmcnt(1)
	v_pk_mul_f32 v[20:21], v[6:7], v[10:11] op_sel:[1,1] op_sel_hi:[1,0]
	v_mul_f32_e32 v22, v9, v13
	v_mul_f32_e32 v24, v9, v12
	s_waitcnt vmcnt(0)
	v_pk_mul_f32 v[30:31], v[2:3], v[14:15] op_sel:[1,1] op_sel_hi:[1,0]
	v_mul_f32_e32 v32, v5, v17
	v_mul_f32_e32 v34, v5, v16
	v_pk_mul_f32 v[18:19], v[6:7], v[10:11]
	v_pk_mul_f32 v[28:29], v[2:3], v[14:15]
	v_pk_fma_f32 v[6:7], v[6:7], v[10:11], v[20:21] op_sel_hi:[0,1,1]
	v_pk_fma_f32 v[10:11], v[8:9], v[12:13], v[22:23] op_sel_hi:[1,1,0] neg_lo:[0,0,1] neg_hi:[0,0,1]
	v_pk_fma_f32 v[12:13], v[8:9], v[12:13], v[24:25] op_sel:[0,1,0] op_sel_hi:[1,0,0]
	v_pk_fma_f32 v[2:3], v[2:3], v[14:15], v[30:31] op_sel_hi:[0,1,1]
	v_pk_fma_f32 v[8:9], v[4:5], v[16:17], v[32:33] op_sel_hi:[1,1,0] neg_lo:[0,0,1] neg_hi:[0,0,1]
	v_pk_fma_f32 v[14:15], v[4:5], v[16:17], v[34:35] op_sel:[0,1,0] op_sel_hi:[1,0,0]
	v_sub_f32_e32 v2, v28, v30
	v_sub_f32_e32 v6, v18, v20
	v_mov_b32_e32 v4, v8
	v_mov_b32_e32 v5, v14
	v_mov_b32_e32 v8, v10
	v_mov_b32_e32 v9, v12
.LBB0_730:
	s_or_b64 exec, exec, s[6:7]
	v_lshl_add_u64 v[10:11], v[26:27], 0, s[26:27]
	s_and_b64 vcc, exec, s[4:5]
	s_mov_b64 s[4:5], -1
	v_cvt_pk_bf16_f32 v6, v6, v7
	v_cvt_pk_bf16_f32 v7, v8, v9
	v_cvt_pk_bf16_f32 v8, v2, v3
	v_cvt_pk_bf16_f32 v9, v4, v5
	global_store_dwordx4 v[10:11], v[6:9], off offset:256 nt
	s_cbranch_vccnz .LBB0_689
	s_andn2_b64 vcc, exec, s[14:15]
	s_cbranch_vccnz .LBB0_688
	s_barrier
	s_branch .LBB0_688

.LBB0_747:
	s_ashr_i32 s39, s38, 31
	s_lshl_b64 s[6:7], s[38:39], 8
	v_lshl_add_u64 v[146:147], s[6:7], 0, v[138:139]
	v_lshlrev_b64 v[144:145], 5, v[146:147]
	v_lshl_add_u64 v[144:145], s[12:13], 0, v[144:145]
	global_load_dwordx2 v[154:155], v[144:145], off offset:16
	v_lshl_or_b32 v144, s65, 8, v1
	v_ashrrev_i32_e32 v145, 31, v144
	v_lshlrev_b64 v[156:157], 13, v[146:147]
	v_lshlrev_b64 v[144:145], 1, v[144:145]
	v_or_b32_e32 v158, 16, v146
	v_mov_b32_e32 v159, v147
	s_waitcnt vmcnt(0)
	v_add_f32_e32 v154, v154, v155
	v_fmamk_f32 v154, v154, 0x3b000000, v152
	v_mul_f32_e32 v155, 0x4f800000, v154
	v_cmp_gt_f32_e32 vcc, s63, v154
	s_nop 1
	v_cndmask_b32_e32 v160, v154, v155, vcc
	v_sqrt_f32_e32 v161, v160
	v_lshl_add_u64 v[154:155], s[14:15], 0, v[156:157]
	v_lshlrev_b64 v[156:157], 5, v[158:159]
	v_lshl_add_u64 v[154:155], v[154:155], 0, v[144:145]
	v_add_u32_e32 v163, -1, v161
	v_add_u32_e32 v164, 1, v161
	v_fma_f32 v165, -v163, v161, v160
	v_fma_f32 v166, -v164, v161, v160
	v_cmp_ge_f32_e64 s[6:7], 0, v165
	v_lshl_add_u64 v[156:157], s[12:13], 0, v[156:157]
	s_nop 0
	v_cndmask_b32_e64 v161, v161, v163, s[6:7]
	v_cmp_lt_f32_e64 s[6:7], 0, v166
	s_nop 1
	v_cndmask_b32_e64 v161, v161, v164, s[6:7]
	v_mul_f32_e32 v163, 0x37800000, v161
	v_cndmask_b32_e32 v161, v161, v163, vcc
	v_cmp_class_f32_e32 vcc, v160, v153
	s_nop 1
	v_cndmask_b32_e32 v160, v161, v160, vcc
	v_div_scale_f32 v161, s[6:7], v160, v160, 1.0
	v_rcp_f32_e32 v163, v161
	v_div_scale_f32 v164, vcc, 1.0, v160, 1.0
	v_fma_f32 v165, -v161, v163, 1.0
	v_fmac_f32_e32 v163, v165, v163
	v_mul_f32_e32 v165, v164, v163
	v_fma_f32 v166, -v161, v165, v164
	v_fmac_f32_e32 v165, v166, v163
	v_fma_f32 v161, -v161, v165, v164
	v_div_fmas_f32 v161, v161, v163, v165
	v_div_fixup_f32 v160, v161, v160, 1.0
	v_pk_mul_f32 v[128:129], v[128:129], v[160:161] op_sel_hi:[1,0]
	v_pk_mul_f32 v[126:127], v[126:127], v[160:161] op_sel_hi:[1,0]
	v_pk_mul_f32 v[124:125], v[124:125], v[160:161] op_sel_hi:[1,0]
	v_pk_mul_f32 v[122:123], v[122:123], v[160:161] op_sel_hi:[1,0]
	v_pk_mul_f32 v[120:121], v[120:121], v[160:161] op_sel_hi:[1,0]
	v_pk_mul_f32 v[118:119], v[118:119], v[160:161] op_sel_hi:[1,0]
	v_pk_mul_f32 v[164:165], v[116:117], v[160:161] op_sel_hi:[1,0]
	v_pk_mul_f32 v[160:161], v[114:115], v[160:161] op_sel_hi:[1,0]
	v_cvt_pk_bf16_f32 v114, v126, v127
	v_cvt_pk_bf16_f32 v115, v128, v129
	v_cvt_pk_bf16_f32 v116, v122, v123
	v_cvt_pk_bf16_f32 v117, v124, v125
	global_store_dwordx4 v[154:155], v[114:117], off nt
	s_nop 1
	v_cvt_pk_bf16_f32 v114, v118, v119
	v_cvt_pk_bf16_f32 v115, v120, v121
	v_cvt_pk_bf16_f32 v116, v160, v161
	v_cvt_pk_bf16_f32 v117, v164, v165
	global_store_dwordx4 v[154:155], v[114:117], off offset:256 nt
	global_load_dwordx2 v[114:115], v[156:157], off offset:16
	v_lshlrev_b64 v[118:119], 13, v[158:159]
	v_or_b32_e32 v116, 32, v146
	v_mov_b32_e32 v117, v147
	v_lshl_add_u64 v[118:119], s[14:15], 0, v[118:119]
	v_lshl_add_u64 v[118:119], v[118:119], 0, v[144:145]
	s_waitcnt vmcnt(0)
	v_add_f32_e32 v114, v114, v115
	v_fmamk_f32 v114, v114, 0x3b000000, v152
	v_mul_f32_e32 v115, 0x4f800000, v114
	v_cmp_gt_f32_e32 vcc, s63, v114
	s_nop 1
	v_cndmask_b32_e32 v120, v114, v115, vcc
	v_sqrt_f32_e32 v121, v120
	v_lshlrev_b64 v[114:115], 5, v[116:117]
	v_lshl_add_u64 v[114:115], s[12:13], 0, v[114:115]
	v_add_u32_e32 v122, -1, v121
	v_add_u32_e32 v123, 1, v121
	v_fma_f32 v124, -v122, v121, v120
	v_fma_f32 v125, -v123, v121, v120
	v_cmp_ge_f32_e64 s[6:7], 0, v124
	s_nop 1
	v_cndmask_b32_e64 v121, v121, v122, s[6:7]
	v_cmp_lt_f32_e64 s[6:7], 0, v125
	s_nop 1
	v_cndmask_b32_e64 v121, v121, v123, s[6:7]
	v_mul_f32_e32 v122, 0x37800000, v121
	v_cndmask_b32_e32 v121, v121, v122, vcc
	v_cmp_class_f32_e32 vcc, v120, v153
	s_nop 1
	v_cndmask_b32_e32 v120, v121, v120, vcc
	v_div_scale_f32 v121, s[6:7], v120, v120, 1.0
	v_rcp_f32_e32 v122, v121
	v_div_scale_f32 v123, vcc, 1.0, v120, 1.0
	v_fma_f32 v124, -v121, v122, 1.0
	v_fmac_f32_e32 v122, v124, v122
	v_mul_f32_e32 v124, v123, v122
	v_fma_f32 v125, -v121, v124, v123
	v_fmac_f32_e32 v124, v125, v122
	v_fma_f32 v121, -v121, v124, v123
	v_div_fmas_f32 v121, v121, v122, v124
	v_div_fixup_f32 v120, v121, v120, 1.0
	v_pk_mul_f32 v[112:113], v[112:113], v[120:121] op_sel_hi:[1,0]
	v_pk_mul_f32 v[110:111], v[110:111], v[120:121] op_sel_hi:[1,0]
	v_pk_mul_f32 v[108:109], v[108:109], v[120:121] op_sel_hi:[1,0]
	v_pk_mul_f32 v[106:107], v[106:107], v[120:121] op_sel_hi:[1,0]
	v_pk_mul_f32 v[104:105], v[104:105], v[120:121] op_sel_hi:[1,0]
	v_pk_mul_f32 v[102:103], v[102:103], v[120:121] op_sel_hi:[1,0]
	v_pk_mul_f32 v[122:123], v[100:101], v[120:121] op_sel_hi:[1,0]
	v_pk_mul_f32 v[120:121], v[98:99], v[120:121] op_sel_hi:[1,0]
	v_cvt_pk_bf16_f32 v98, v110, v111
	v_cvt_pk_bf16_f32 v99, v112, v113
	v_cvt_pk_bf16_f32 v100, v106, v107
	v_cvt_pk_bf16_f32 v101, v108, v109
	global_store_dwordx4 v[118:119], v[98:101], off nt
	s_nop 1
	v_cvt_pk_bf16_f32 v98, v102, v103
	v_cvt_pk_bf16_f32 v99, v104, v105
	v_cvt_pk_bf16_f32 v100, v120, v121
	v_cvt_pk_bf16_f32 v101, v122, v123
	global_store_dwordx4 v[118:119], v[98:101], off offset:256 nt
	global_load_dwordx2 v[98:99], v[114:115], off offset:16
	v_lshlrev_b64 v[102:103], 13, v[116:117]
	v_or_b32_e32 v100, 48, v146
	v_mov_b32_e32 v101, v147
	v_lshl_add_u64 v[102:103], s[14:15], 0, v[102:103]
	v_lshl_add_u64 v[102:103], v[102:103], 0, v[144:145]
	s_waitcnt vmcnt(0)
	v_add_f32_e32 v98, v98, v99
	v_fmamk_f32 v98, v98, 0x3b000000, v152
	v_mul_f32_e32 v99, 0x4f800000, v98
	v_cmp_gt_f32_e32 vcc, s63, v98
	s_nop 1
	v_cndmask_b32_e32 v104, v98, v99, vcc
	v_sqrt_f32_e32 v105, v104
	v_lshlrev_b64 v[98:99], 5, v[100:101]
	v_lshl_add_u64 v[98:99], s[12:13], 0, v[98:99]
	v_add_u32_e32 v106, -1, v105
	v_add_u32_e32 v107, 1, v105
	v_fma_f32 v108, -v106, v105, v104
	v_fma_f32 v109, -v107, v105, v104
	v_cmp_ge_f32_e64 s[6:7], 0, v108
	s_nop 1
	v_cndmask_b32_e64 v105, v105, v106, s[6:7]
	v_cmp_lt_f32_e64 s[6:7], 0, v109
	s_nop 1
	v_cndmask_b32_e64 v105, v105, v107, s[6:7]
	v_mul_f32_e32 v106, 0x37800000, v105
	v_cndmask_b32_e32 v105, v105, v106, vcc
	v_cmp_class_f32_e32 vcc, v104, v153
	s_nop 1
	v_cndmask_b32_e32 v104, v105, v104, vcc
	v_div_scale_f32 v105, s[6:7], v104, v104, 1.0
	v_rcp_f32_e32 v106, v105
	v_div_scale_f32 v107, vcc, 1.0, v104, 1.0
	v_fma_f32 v108, -v105, v106, 1.0
	v_fmac_f32_e32 v106, v108, v106
	v_mul_f32_e32 v108, v107, v106
	v_fma_f32 v109, -v105, v108, v107
	v_fmac_f32_e32 v108, v109, v106
	v_fma_f32 v105, -v105, v108, v107
	v_div_fmas_f32 v105, v105, v106, v108
	v_div_fixup_f32 v104, v105, v104, 1.0
	v_pk_mul_f32 v[96:97], v[96:97], v[104:105] op_sel_hi:[1,0]
	v_pk_mul_f32 v[94:95], v[94:95], v[104:105] op_sel_hi:[1,0]
	v_pk_mul_f32 v[92:93], v[92:93], v[104:105] op_sel_hi:[1,0]
	v_pk_mul_f32 v[90:91], v[90:91], v[104:105] op_sel_hi:[1,0]
	v_pk_mul_f32 v[88:89], v[88:89], v[104:105] op_sel_hi:[1,0]
	v_pk_mul_f32 v[86:87], v[86:87], v[104:105] op_sel_hi:[1,0]
	v_pk_mul_f32 v[106:107], v[84:85], v[104:105] op_sel_hi:[1,0]
	v_pk_mul_f32 v[104:105], v[82:83], v[104:105] op_sel_hi:[1,0]
	v_cvt_pk_bf16_f32 v82, v94, v95
	v_cvt_pk_bf16_f32 v83, v96, v97
	v_cvt_pk_bf16_f32 v84, v90, v91
	v_cvt_pk_bf16_f32 v85, v92, v93
	global_store_dwordx4 v[102:103], v[82:85], off nt
	s_nop 1
	v_cvt_pk_bf16_f32 v82, v86, v87
	v_cvt_pk_bf16_f32 v83, v88, v89
	v_cvt_pk_bf16_f32 v84, v104, v105
	v_cvt_pk_bf16_f32 v85, v106, v107
	global_store_dwordx4 v[102:103], v[82:85], off offset:256 nt
	global_load_dwordx2 v[82:83], v[98:99], off offset:16
	v_lshlrev_b64 v[86:87], 13, v[100:101]
	v_lshl_add_u64 v[84:85], v[146:147], 0, s[16:17]
	v_lshl_add_u64 v[86:87], s[14:15], 0, v[86:87]
	v_lshl_add_u64 v[86:87], v[86:87], 0, v[144:145]
	s_waitcnt vmcnt(0)
	v_add_f32_e32 v82, v82, v83
	v_fmamk_f32 v82, v82, 0x3b000000, v152
	v_mul_f32_e32 v83, 0x4f800000, v82
	v_cmp_gt_f32_e32 vcc, s63, v82
	s_nop 1
	v_cndmask_b32_e32 v88, v82, v83, vcc
	v_sqrt_f32_e32 v89, v88
	v_lshlrev_b64 v[82:83], 5, v[84:85]
	v_lshl_add_u64 v[82:83], s[12:13], 0, v[82:83]
	v_add_u32_e32 v90, -1, v89
	v_add_u32_e32 v91, 1, v89
	v_fma_f32 v92, -v90, v89, v88
	v_fma_f32 v93, -v91, v89, v88
	v_cmp_ge_f32_e64 s[6:7], 0, v92
	s_nop 1
	v_cndmask_b32_e64 v89, v89, v90, s[6:7]
	v_cmp_lt_f32_e64 s[6:7], 0, v93
	s_nop 1
	v_cndmask_b32_e64 v89, v89, v91, s[6:7]
	v_mul_f32_e32 v90, 0x37800000, v89
	v_cndmask_b32_e32 v89, v89, v90, vcc
	v_cmp_class_f32_e32 vcc, v88, v153
	s_nop 1
	v_cndmask_b32_e32 v88, v89, v88, vcc
	v_div_scale_f32 v89, s[6:7], v88, v88, 1.0
	v_rcp_f32_e32 v90, v89
	v_div_scale_f32 v91, vcc, 1.0, v88, 1.0
	v_fma_f32 v92, -v89, v90, 1.0
	v_fmac_f32_e32 v90, v92, v90
	v_mul_f32_e32 v92, v91, v90
	v_fma_f32 v93, -v89, v92, v91
	v_fmac_f32_e32 v92, v93, v90
	v_fma_f32 v89, -v89, v92, v91
	v_div_fmas_f32 v89, v89, v90, v92
	v_div_fixup_f32 v88, v89, v88, 1.0
	v_pk_mul_f32 v[80:81], v[80:81], v[88:89] op_sel_hi:[1,0]
	v_pk_mul_f32 v[78:79], v[78:79], v[88:89] op_sel_hi:[1,0]
	v_pk_mul_f32 v[76:77], v[76:77], v[88:89] op_sel_hi:[1,0]
	v_pk_mul_f32 v[74:75], v[74:75], v[88:89] op_sel_hi:[1,0]
	v_pk_mul_f32 v[72:73], v[72:73], v[88:89] op_sel_hi:[1,0]
	v_pk_mul_f32 v[70:71], v[70:71], v[88:89] op_sel_hi:[1,0]
	v_pk_mul_f32 v[90:91], v[68:69], v[88:89] op_sel_hi:[1,0]
	v_pk_mul_f32 v[88:89], v[66:67], v[88:89] op_sel_hi:[1,0]
	v_cvt_pk_bf16_f32 v66, v78, v79
	v_cvt_pk_bf16_f32 v67, v80, v81
	v_cvt_pk_bf16_f32 v68, v74, v75
	v_cvt_pk_bf16_f32 v69, v76, v77
	global_store_dwordx4 v[86:87], v[66:69], off nt
	s_nop 1
	v_cvt_pk_bf16_f32 v66, v70, v71
	v_cvt_pk_bf16_f32 v67, v72, v73
	v_cvt_pk_bf16_f32 v68, v88, v89
	v_cvt_pk_bf16_f32 v69, v90, v91
	global_store_dwordx4 v[86:87], v[66:69], off offset:256 nt
	global_load_dwordx2 v[66:67], v[82:83], off offset:16
	v_lshlrev_b64 v[70:71], 13, v[84:85]
	v_lshl_add_u64 v[68:69], v[146:147], 0, s[22:23]
	v_lshl_add_u64 v[70:71], s[14:15], 0, v[70:71]
	v_lshl_add_u64 v[70:71], v[70:71], 0, v[144:145]
	s_waitcnt vmcnt(0)
	v_add_f32_e32 v66, v66, v67
	v_fmamk_f32 v66, v66, 0x3b000000, v152
	v_mul_f32_e32 v67, 0x4f800000, v66
	v_cmp_gt_f32_e32 vcc, s63, v66
	s_nop 1
	v_cndmask_b32_e32 v72, v66, v67, vcc
	v_sqrt_f32_e32 v73, v72
	v_lshlrev_b64 v[66:67], 5, v[68:69]
	v_lshl_add_u64 v[66:67], s[12:13], 0, v[66:67]
	v_add_u32_e32 v74, -1, v73
	v_add_u32_e32 v75, 1, v73
	v_fma_f32 v76, -v74, v73, v72
	v_fma_f32 v77, -v75, v73, v72
	v_cmp_ge_f32_e64 s[6:7], 0, v76
	s_nop 1
	v_cndmask_b32_e64 v73, v73, v74, s[6:7]
	v_cmp_lt_f32_e64 s[6:7], 0, v77
	s_nop 1
	v_cndmask_b32_e64 v73, v73, v75, s[6:7]
	v_mul_f32_e32 v74, 0x37800000, v73
	v_cndmask_b32_e32 v73, v73, v74, vcc
	v_cmp_class_f32_e32 vcc, v72, v153
	s_nop 1
	v_cndmask_b32_e32 v72, v73, v72, vcc
	v_div_scale_f32 v73, s[6:7], v72, v72, 1.0
	v_rcp_f32_e32 v74, v73
	v_div_scale_f32 v75, vcc, 1.0, v72, 1.0
	v_fma_f32 v76, -v73, v74, 1.0
	v_fmac_f32_e32 v74, v76, v74
	v_mul_f32_e32 v76, v75, v74
	v_fma_f32 v77, -v73, v76, v75
	v_fmac_f32_e32 v76, v77, v74
	v_fma_f32 v73, -v73, v76, v75
	v_div_fmas_f32 v73, v73, v74, v76
	v_div_fixup_f32 v72, v73, v72, 1.0
	v_pk_mul_f32 v[64:65], v[64:65], v[72:73] op_sel_hi:[1,0]
	v_pk_mul_f32 v[62:63], v[62:63], v[72:73] op_sel_hi:[1,0]
	v_pk_mul_f32 v[60:61], v[60:61], v[72:73] op_sel_hi:[1,0]
	v_pk_mul_f32 v[58:59], v[58:59], v[72:73] op_sel_hi:[1,0]
	v_pk_mul_f32 v[56:57], v[56:57], v[72:73] op_sel_hi:[1,0]
	v_pk_mul_f32 v[54:55], v[54:55], v[72:73] op_sel_hi:[1,0]
	v_pk_mul_f32 v[74:75], v[52:53], v[72:73] op_sel_hi:[1,0]
	v_pk_mul_f32 v[72:73], v[50:51], v[72:73] op_sel_hi:[1,0]
	v_cvt_pk_bf16_f32 v50, v62, v63
	v_cvt_pk_bf16_f32 v51, v64, v65
	v_cvt_pk_bf16_f32 v52, v58, v59
	v_cvt_pk_bf16_f32 v53, v60, v61
	global_store_dwordx4 v[70:71], v[50:53], off nt
	s_nop 1
	v_cvt_pk_bf16_f32 v50, v54, v55
	v_cvt_pk_bf16_f32 v51, v56, v57
	v_cvt_pk_bf16_f32 v52, v72, v73
	v_cvt_pk_bf16_f32 v53, v74, v75
	global_store_dwordx4 v[70:71], v[50:53], off offset:256 nt
	global_load_dwordx2 v[50:51], v[66:67], off offset:16
	v_lshlrev_b64 v[54:55], 13, v[68:69]
	v_lshl_add_u64 v[52:53], v[146:147], 0, s[24:25]
	v_lshl_add_u64 v[54:55], s[14:15], 0, v[54:55]
	v_lshl_add_u64 v[54:55], v[54:55], 0, v[144:145]
	s_waitcnt vmcnt(0)
	v_add_f32_e32 v50, v50, v51
	v_fmamk_f32 v50, v50, 0x3b000000, v152
	v_mul_f32_e32 v51, 0x4f800000, v50
	v_cmp_gt_f32_e32 vcc, s63, v50
	s_nop 1
	v_cndmask_b32_e32 v56, v50, v51, vcc
	v_sqrt_f32_e32 v57, v56
	v_lshlrev_b64 v[50:51], 5, v[52:53]
	v_lshl_add_u64 v[50:51], s[12:13], 0, v[50:51]
	v_add_u32_e32 v58, -1, v57
	v_add_u32_e32 v59, 1, v57
	v_fma_f32 v60, -v58, v57, v56
	v_fma_f32 v61, -v59, v57, v56
	v_cmp_ge_f32_e64 s[6:7], 0, v60
	s_nop 1
	v_cndmask_b32_e64 v57, v57, v58, s[6:7]
	v_cmp_lt_f32_e64 s[6:7], 0, v61
	s_nop 1
	v_cndmask_b32_e64 v57, v57, v59, s[6:7]
	v_mul_f32_e32 v58, 0x37800000, v57
	v_cndmask_b32_e32 v57, v57, v58, vcc
	v_cmp_class_f32_e32 vcc, v56, v153
	s_nop 1
	v_cndmask_b32_e32 v56, v57, v56, vcc
	v_div_scale_f32 v57, s[6:7], v56, v56, 1.0
	v_rcp_f32_e32 v58, v57
	v_div_scale_f32 v59, vcc, 1.0, v56, 1.0
	v_fma_f32 v60, -v57, v58, 1.0
	v_fmac_f32_e32 v58, v60, v58
	v_mul_f32_e32 v60, v59, v58
	v_fma_f32 v61, -v57, v60, v59
	v_fmac_f32_e32 v60, v61, v58
	v_fma_f32 v57, -v57, v60, v59
	v_div_fmas_f32 v57, v57, v58, v60
	v_div_fixup_f32 v56, v57, v56, 1.0
	v_pk_mul_f32 v[48:49], v[48:49], v[56:57] op_sel_hi:[1,0]
	v_pk_mul_f32 v[46:47], v[46:47], v[56:57] op_sel_hi:[1,0]
	v_pk_mul_f32 v[44:45], v[44:45], v[56:57] op_sel_hi:[1,0]
	v_pk_mul_f32 v[42:43], v[42:43], v[56:57] op_sel_hi:[1,0]
	v_pk_mul_f32 v[40:41], v[40:41], v[56:57] op_sel_hi:[1,0]
	v_pk_mul_f32 v[38:39], v[38:39], v[56:57] op_sel_hi:[1,0]
	v_pk_mul_f32 v[58:59], v[36:37], v[56:57] op_sel_hi:[1,0]
	v_pk_mul_f32 v[56:57], v[34:35], v[56:57] op_sel_hi:[1,0]
	v_cvt_pk_bf16_f32 v34, v46, v47
	v_cvt_pk_bf16_f32 v35, v48, v49
	v_cvt_pk_bf16_f32 v36, v42, v43
	v_cvt_pk_bf16_f32 v37, v44, v45
	global_store_dwordx4 v[54:55], v[34:37], off nt
	s_nop 1
	v_cvt_pk_bf16_f32 v34, v38, v39
	v_cvt_pk_bf16_f32 v35, v40, v41
	v_cvt_pk_bf16_f32 v36, v56, v57
	v_cvt_pk_bf16_f32 v37, v58, v59
	global_store_dwordx4 v[54:55], v[34:37], off offset:256 nt
	global_load_dwordx2 v[34:35], v[50:51], off offset:16
	v_lshlrev_b64 v[38:39], 13, v[52:53]
	v_lshl_add_u64 v[36:37], v[146:147], 0, s[26:27]
	v_lshl_add_u64 v[38:39], s[14:15], 0, v[38:39]
	v_lshl_add_u64 v[38:39], v[38:39], 0, v[144:145]
	s_waitcnt vmcnt(0)
	v_add_f32_e32 v34, v34, v35
	v_fmamk_f32 v34, v34, 0x3b000000, v152
	v_mul_f32_e32 v35, 0x4f800000, v34
	v_cmp_gt_f32_e32 vcc, s63, v34
	s_nop 1
	v_cndmask_b32_e32 v40, v34, v35, vcc
	v_sqrt_f32_e32 v41, v40
	v_lshlrev_b64 v[34:35], 5, v[36:37]
	v_lshl_add_u64 v[34:35], s[12:13], 0, v[34:35]
	v_add_u32_e32 v42, -1, v41
	v_add_u32_e32 v43, 1, v41
	v_fma_f32 v44, -v42, v41, v40
	v_fma_f32 v45, -v43, v41, v40
	v_cmp_ge_f32_e64 s[6:7], 0, v44
	s_nop 1
	v_cndmask_b32_e64 v41, v41, v42, s[6:7]
	v_cmp_lt_f32_e64 s[6:7], 0, v45
	s_nop 1
	v_cndmask_b32_e64 v41, v41, v43, s[6:7]
	v_mul_f32_e32 v42, 0x37800000, v41
	v_cndmask_b32_e32 v41, v41, v42, vcc
	v_cmp_class_f32_e32 vcc, v40, v153
	s_nop 1
	v_cndmask_b32_e32 v40, v41, v40, vcc
	v_div_scale_f32 v41, s[6:7], v40, v40, 1.0
	v_rcp_f32_e32 v42, v41
	v_div_scale_f32 v43, vcc, 1.0, v40, 1.0
	v_fma_f32 v44, -v41, v42, 1.0
	v_fmac_f32_e32 v42, v44, v42
	v_mul_f32_e32 v44, v43, v42
	v_fma_f32 v45, -v41, v44, v43
	v_fmac_f32_e32 v44, v45, v42
	v_fma_f32 v41, -v41, v44, v43
	v_div_fmas_f32 v41, v41, v42, v44
	v_div_fixup_f32 v40, v41, v40, 1.0
	v_pk_mul_f32 v[32:33], v[32:33], v[40:41] op_sel_hi:[1,0]
	v_pk_mul_f32 v[30:31], v[30:31], v[40:41] op_sel_hi:[1,0]
	v_pk_mul_f32 v[28:29], v[28:29], v[40:41] op_sel_hi:[1,0]
	v_pk_mul_f32 v[26:27], v[26:27], v[40:41] op_sel_hi:[1,0]
	v_pk_mul_f32 v[24:25], v[24:25], v[40:41] op_sel_hi:[1,0]
	v_pk_mul_f32 v[22:23], v[22:23], v[40:41] op_sel_hi:[1,0]
	v_pk_mul_f32 v[42:43], v[20:21], v[40:41] op_sel_hi:[1,0]
	v_pk_mul_f32 v[40:41], v[18:19], v[40:41] op_sel_hi:[1,0]
	v_cvt_pk_bf16_f32 v18, v30, v31
	v_cvt_pk_bf16_f32 v19, v32, v33
	v_cvt_pk_bf16_f32 v20, v26, v27
	v_cvt_pk_bf16_f32 v21, v28, v29
	global_store_dwordx4 v[38:39], v[18:21], off nt
	s_nop 1
	v_cvt_pk_bf16_f32 v18, v22, v23
	v_cvt_pk_bf16_f32 v19, v24, v25
	v_cvt_pk_bf16_f32 v20, v40, v41
	v_cvt_pk_bf16_f32 v21, v42, v43
	global_store_dwordx4 v[38:39], v[18:21], off offset:256 nt
	global_load_dwordx2 v[18:19], v[34:35], off offset:16
	s_waitcnt vmcnt(0)
	v_add_f32_e32 v18, v18, v19
	v_fmamk_f32 v18, v18, 0x3b000000, v152
	v_mul_f32_e32 v19, 0x4f800000, v18
	v_cmp_gt_f32_e32 vcc, s63, v18
	s_nop 1
	v_cndmask_b32_e32 v20, v18, v19, vcc
	v_sqrt_f32_e32 v21, v20
	v_lshlrev_b64 v[18:19], 13, v[36:37]
	v_lshl_add_u64 v[18:19], s[14:15], 0, v[18:19]
	v_lshl_add_u64 v[18:19], v[18:19], 0, v[144:145]
	v_add_u32_e32 v22, -1, v21
	v_add_u32_e32 v23, 1, v21
	v_fma_f32 v24, -v22, v21, v20
	v_fma_f32 v25, -v23, v21, v20
	v_cmp_ge_f32_e64 s[6:7], 0, v24
	s_nop 1
	v_cndmask_b32_e64 v21, v21, v22, s[6:7]
	v_cmp_lt_f32_e64 s[6:7], 0, v25
	s_nop 1
	v_cndmask_b32_e64 v21, v21, v23, s[6:7]
	v_mul_f32_e32 v22, 0x37800000, v21
	v_cndmask_b32_e32 v21, v21, v22, vcc
	v_cmp_class_f32_e32 vcc, v20, v153
	s_nop 1
	v_cndmask_b32_e32 v20, v21, v20, vcc
	v_div_scale_f32 v21, s[6:7], v20, v20, 1.0
	v_rcp_f32_e32 v22, v21
	v_div_scale_f32 v23, vcc, 1.0, v20, 1.0
	v_fma_f32 v24, -v21, v22, 1.0
	v_fmac_f32_e32 v22, v24, v22
	v_mul_f32_e32 v24, v23, v22
	v_fma_f32 v25, -v21, v24, v23
	v_fmac_f32_e32 v24, v25, v22
	v_fma_f32 v21, -v21, v24, v23
	v_div_fmas_f32 v21, v21, v22, v24
	v_div_fixup_f32 v20, v21, v20, 1.0
	s_and_b64 vcc, exec, s[4:5]
	v_pk_mul_f32 v[16:17], v[16:17], v[20:21] op_sel_hi:[1,0]
	v_pk_mul_f32 v[14:15], v[14:15], v[20:21] op_sel_hi:[1,0]
	v_pk_mul_f32 v[12:13], v[12:13], v[20:21] op_sel_hi:[1,0]
	v_pk_mul_f32 v[10:11], v[10:11], v[20:21] op_sel_hi:[1,0]
	v_pk_mul_f32 v[8:9], v[8:9], v[20:21] op_sel_hi:[1,0]
	v_pk_mul_f32 v[6:7], v[6:7], v[20:21] op_sel_hi:[1,0]
	v_pk_mul_f32 v[22:23], v[4:5], v[20:21] op_sel_hi:[1,0]
	v_pk_mul_f32 v[20:21], v[2:3], v[20:21] op_sel_hi:[1,0]
	v_cvt_pk_bf16_f32 v2, v14, v15
	v_cvt_pk_bf16_f32 v3, v16, v17
	v_cvt_pk_bf16_f32 v4, v10, v11
	v_cvt_pk_bf16_f32 v5, v12, v13
	s_mov_b64 s[4:5], -1
	global_store_dwordx4 v[18:19], v[2:5], off nt
	s_nop 1
	v_cvt_pk_bf16_f32 v2, v6, v7
	v_cvt_pk_bf16_f32 v3, v8, v9
	v_cvt_pk_bf16_f32 v4, v20, v21
	v_cvt_pk_bf16_f32 v5, v22, v23
	global_store_dwordx4 v[18:19], v[2:5], off offset:256 nt
	s_cbranch_vccnz .LBB0_738
	s_andn2_b64 vcc, exec, s[8:9]
	s_cbranch_vccnz .LBB0_737
	s_barrier
	s_branch .LBB0_737

.LBB0_804:
	s_or_b64 exec, exec, s[6:7]
	s_waitcnt lgkmcnt(0)
	v_add_u32_e32 v74, s71, v148
	ds_read_b128 v[66:69], v74
	ds_read_b128 v[70:73], v74 offset:32
	s_lshl_b64 s[6:7], s[28:29], 13
	s_add_u32 s4, s42, s6
	s_addc_u32 s5, s43, s7
	s_lshl_b32 s28, s69, 1
	s_add_u32 s4, s4, s28
	s_addc_u32 s5, s5, 0
	s_waitcnt lgkmcnt(1)
	v_rcp_f32_e32 v75, v66
	s_add_u32 s6, s0, s6
	s_addc_u32 s7, s1, s7
	v_rcp_f32_e32 v76, v67
	v_rcp_f32_e32 v77, v68
	v_rcp_f32_e32 v78, v69
	s_waitcnt lgkmcnt(0)
	v_rcp_f32_e32 v79, v70
	ds_read_b128 v[66:69], v74 offset:64
	v_rcp_f32_e32 v80, v71
	v_rcp_f32_e32 v81, v72
	v_rcp_f32_e32 v82, v73
	ds_read_b128 v[70:73], v74 offset:96
	v_mul_u32_u24_e32 v74, 0x440, v155
	s_add_u32 s6, s6, s28
	s_mulk_i32 s68, 0x2200
	v_lshl_or_b32 v74, v154, 1, v74
	s_addc_u32 s7, s7, 0
	s_waitcnt lgkmcnt(0)
	s_barrier
	s_add_i32 s28, s68, 0
	v_mul_f32_e32 v2, v2, v75
	v_add_u32_e32 v74, s28, v74
	v_cvt_pk_bf16_f32 v2, v2, v147
	ds_write_b16 v74, v2
	v_mul_f32_e32 v2, v50, v75
	v_cvt_pk_bf16_f32 v2, v2, v147
	ds_write_b16 v74, v2 offset:64
	v_mul_f32_e32 v2, v34, v75
	v_cvt_pk_bf16_f32 v2, v2, v147
	ds_write_b16 v74, v2 offset:128
	v_mul_f32_e32 v2, v18, v75
	v_cvt_pk_bf16_f32 v2, v2, v147
	ds_write_b16 v74, v2 offset:192
	v_mul_f32_e32 v2, v3, v76
	v_cvt_pk_bf16_f32 v2, v2, v147
	ds_write_b16 v74, v2 offset:272
	v_mul_f32_e32 v2, v51, v76
	v_cvt_pk_bf16_f32 v2, v2, v147
	ds_write_b16 v74, v2 offset:336
	v_mul_f32_e32 v2, v35, v76
	v_cvt_pk_bf16_f32 v2, v2, v147
	ds_write_b16 v74, v2 offset:400
	v_mul_f32_e32 v2, v19, v76
	v_cvt_pk_bf16_f32 v2, v2, v147
	ds_write_b16 v74, v2 offset:464
	v_mul_f32_e32 v2, v4, v77
	v_cvt_pk_bf16_f32 v2, v2, v147
	ds_write_b16 v74, v2 offset:544
	v_mul_f32_e32 v2, v52, v77
	v_cvt_pk_bf16_f32 v2, v2, v147
	ds_write_b16 v74, v2 offset:608
	v_mul_f32_e32 v2, v36, v77
	v_cvt_pk_bf16_f32 v2, v2, v147
	ds_write_b16 v74, v2 offset:672
	v_mul_f32_e32 v2, v20, v77
	v_cvt_pk_bf16_f32 v2, v2, v147
	ds_write_b16 v74, v2 offset:736
	v_mul_f32_e32 v2, v5, v78
	v_cvt_pk_bf16_f32 v2, v2, v147
	ds_write_b16 v74, v2 offset:816
	v_mul_f32_e32 v2, v53, v78
	v_cvt_pk_bf16_f32 v2, v2, v147
	ds_write_b16 v74, v2 offset:880
	v_mul_f32_e32 v2, v37, v78
	v_cvt_pk_bf16_f32 v2, v2, v147
	ds_write_b16 v74, v2 offset:944
	v_mul_f32_e32 v2, v21, v78
	v_cvt_pk_bf16_f32 v2, v2, v147
	ds_write_b16 v74, v2 offset:1008
	v_mul_f32_e32 v2, v6, v79
	v_cvt_pk_bf16_f32 v2, v2, v147
	ds_write_b16 v74, v2 offset:2176
	v_mul_f32_e32 v2, v54, v79
	v_cvt_pk_bf16_f32 v2, v2, v147
	ds_write_b16 v74, v2 offset:2240
	v_mul_f32_e32 v2, v38, v79
	v_cvt_pk_bf16_f32 v2, v2, v147
	ds_write_b16 v74, v2 offset:2304
	v_mul_f32_e32 v2, v22, v79
	v_cvt_pk_bf16_f32 v2, v2, v147
	ds_write_b16 v74, v2 offset:2368
	v_mul_f32_e32 v2, v7, v80
	v_cvt_pk_bf16_f32 v2, v2, v147
	ds_write_b16 v74, v2 offset:2448
	v_mul_f32_e32 v2, v55, v80
	v_cvt_pk_bf16_f32 v2, v2, v147
	ds_write_b16 v74, v2 offset:2512
	v_mul_f32_e32 v2, v39, v80
	v_cvt_pk_bf16_f32 v2, v2, v147
	ds_write_b16 v74, v2 offset:2576
	v_mul_f32_e32 v2, v23, v80
	v_cvt_pk_bf16_f32 v2, v2, v147
	ds_write_b16 v74, v2 offset:2640
	v_mul_f32_e32 v2, v8, v81
	v_cvt_pk_bf16_f32 v2, v2, v147
	ds_write_b16 v74, v2 offset:2720
	v_mul_f32_e32 v2, v56, v81
	v_cvt_pk_bf16_f32 v2, v2, v147
	ds_write_b16 v74, v2 offset:2784
	v_mul_f32_e32 v2, v40, v81
	v_cvt_pk_bf16_f32 v2, v2, v147
	ds_write_b16 v74, v2 offset:2848
	v_mul_f32_e32 v2, v24, v81
	v_cvt_pk_bf16_f32 v2, v2, v147
	ds_write_b16 v74, v2 offset:2912
	v_mul_f32_e32 v2, v9, v82
	v_cvt_pk_bf16_f32 v2, v2, v147
	ds_write_b16 v74, v2 offset:2992
	v_mul_f32_e32 v2, v57, v82
	v_cvt_pk_bf16_f32 v2, v2, v147
	v_rcp_f32_e32 v66, v66
	ds_write_b16 v74, v2 offset:3056
	v_mul_f32_e32 v2, v41, v82
	v_cvt_pk_bf16_f32 v2, v2, v147
	ds_write_b16 v74, v2 offset:3120
	v_mul_f32_e32 v2, v25, v82
	v_cvt_pk_bf16_f32 v2, v2, v147
	ds_write_b16 v74, v2 offset:3184
	v_mul_f32_e32 v2, v10, v66
	v_cvt_pk_bf16_f32 v2, v2, v147
	ds_write_b16 v74, v2 offset:4352
	v_mul_f32_e32 v2, v58, v66
	v_cvt_pk_bf16_f32 v2, v2, v147
	v_rcp_f32_e32 v67, v67
	ds_write_b16 v74, v2 offset:4416
	v_mul_f32_e32 v2, v42, v66
	v_cvt_pk_bf16_f32 v2, v2, v147
	ds_write_b16 v74, v2 offset:4480
	v_mul_f32_e32 v2, v26, v66
	v_cvt_pk_bf16_f32 v2, v2, v147
	ds_write_b16 v74, v2 offset:4544
	v_mul_f32_e32 v2, v11, v67
	v_cvt_pk_bf16_f32 v2, v2, v147
	ds_write_b16 v74, v2 offset:4624
	v_mul_f32_e32 v2, v59, v67
	v_cvt_pk_bf16_f32 v2, v2, v147
	v_rcp_f32_e32 v68, v68
	ds_write_b16 v74, v2 offset:4688
	v_mul_f32_e32 v2, v43, v67
	v_cvt_pk_bf16_f32 v2, v2, v147
	ds_write_b16 v74, v2 offset:4752
	v_mul_f32_e32 v2, v27, v67
	v_cvt_pk_bf16_f32 v2, v2, v147
	ds_write_b16 v74, v2 offset:4816
	v_mul_f32_e32 v2, v12, v68
	v_cvt_pk_bf16_f32 v2, v2, v147
	ds_write_b16 v74, v2 offset:4896
	v_mul_f32_e32 v2, v60, v68
	v_cvt_pk_bf16_f32 v2, v2, v147
	v_rcp_f32_e32 v69, v69
	ds_write_b16 v74, v2 offset:4960
	v_mul_f32_e32 v2, v44, v68
	v_cvt_pk_bf16_f32 v2, v2, v147
	ds_write_b16 v74, v2 offset:5024
	v_mul_f32_e32 v2, v28, v68
	v_cvt_pk_bf16_f32 v2, v2, v147
	ds_write_b16 v74, v2 offset:5088
	v_mul_f32_e32 v2, v13, v69
	v_cvt_pk_bf16_f32 v2, v2, v147
	ds_write_b16 v74, v2 offset:5168
	v_mul_f32_e32 v2, v61, v69
	v_cvt_pk_bf16_f32 v2, v2, v147
	v_rcp_f32_e32 v70, v70
	ds_write_b16 v74, v2 offset:5232
	v_mul_f32_e32 v2, v45, v69
	v_cvt_pk_bf16_f32 v2, v2, v147
	ds_write_b16 v74, v2 offset:5296
	v_mul_f32_e32 v2, v29, v69
	v_cvt_pk_bf16_f32 v2, v2, v147
	ds_write_b16 v74, v2 offset:5360
	v_mul_f32_e32 v2, v14, v70
	v_cvt_pk_bf16_f32 v2, v2, v147
	ds_write_b16 v74, v2 offset:6528
	v_mul_f32_e32 v2, v62, v70
	v_cvt_pk_bf16_f32 v2, v2, v147
	v_rcp_f32_e32 v71, v71
	ds_write_b16 v74, v2 offset:6592
	v_mul_f32_e32 v2, v46, v70
	v_cvt_pk_bf16_f32 v2, v2, v147
	ds_write_b16 v74, v2 offset:6656
	v_mul_f32_e32 v2, v30, v70
	v_cvt_pk_bf16_f32 v2, v2, v147
	ds_write_b16 v74, v2 offset:6720
	v_mul_f32_e32 v2, v15, v71
	v_cvt_pk_bf16_f32 v2, v2, v147
	ds_write_b16 v74, v2 offset:6800
	v_mul_f32_e32 v2, v63, v71
	v_cvt_pk_bf16_f32 v2, v2, v147
	v_rcp_f32_e32 v72, v72
	ds_write_b16 v74, v2 offset:6864
	v_mul_f32_e32 v2, v47, v71
	v_cvt_pk_bf16_f32 v2, v2, v147
	ds_write_b16 v74, v2 offset:6928
	v_mul_f32_e32 v2, v31, v71
	v_cvt_pk_bf16_f32 v2, v2, v147
	ds_write_b16 v74, v2 offset:6992
	v_mul_f32_e32 v2, v16, v72
	v_cvt_pk_bf16_f32 v2, v2, v147
	ds_write_b16 v74, v2 offset:7072
	v_mul_f32_e32 v2, v64, v72
	v_cvt_pk_bf16_f32 v2, v2, v147
	v_rcp_f32_e32 v73, v73
	ds_write_b16 v74, v2 offset:7136
	v_mul_f32_e32 v2, v48, v72
	v_cvt_pk_bf16_f32 v2, v2, v147
	ds_write_b16 v74, v2 offset:7200
	v_mul_f32_e32 v2, v32, v72
	v_cvt_pk_bf16_f32 v2, v2, v147
	ds_write_b16 v74, v2 offset:7264
	v_mul_f32_e32 v2, v17, v73
	v_cvt_pk_bf16_f32 v2, v2, v147
	ds_write_b16 v74, v2 offset:7344
	v_mul_f32_e32 v2, v65, v73
	v_cvt_pk_bf16_f32 v2, v2, v147
	ds_write_b16 v74, v2 offset:7408
	v_mul_f32_e32 v2, v49, v73
	v_cvt_pk_bf16_f32 v2, v2, v147
	ds_write_b16 v74, v2 offset:7472
	v_mul_f32_e32 v2, v33, v73
	v_cvt_pk_bf16_f32 v2, v2, v147
	ds_write_b16 v74, v2 offset:7536
	s_waitcnt lgkmcnt(0)
	s_add_i32 s53, s53, 1
	v_ashrrev_i32_e32 v16, 4, v149
	v_add_u32_e32 v2, s65, v16
	v_ashrrev_i32_e32 v3, 31, v2
	v_lshlrev_b64 v[2:3], 13, v[2:3]
	v_lshlrev_b32_e32 v4, 4, v149
	v_and_b32_e32 v146, 0xf0, v4
	v_lshl_add_u64 v[4:5], s[6:7], 0, v[2:3]
	v_lshl_add_u64 v[36:37], v[4:5], 0, v[146:147]
	global_load_dwordx4 v[4:7], v[36:37], off
	v_add_co_u32_e32 v8, vcc, s59, v36
	v_mul_lo_u32 v16, v16, s60
	s_nop 0
	v_addc_co_u32_e32 v9, vcc, 0, v37, vcc
	global_load_dwordx4 v[8:11], v[8:9], off
	v_add_co_u32_e32 v12, vcc, s56, v36
	v_add3_u32 v38, s28, v146, v16
	s_nop 0
	v_addc_co_u32_e32 v13, vcc, 0, v37, vcc
	global_load_dwordx4 v[12:15], v[12:13], off
	v_add_co_u32_e32 v20, vcc, s58, v36
	ds_read_b128 v[16:19], v38
	s_nop 0
	v_addc_co_u32_e32 v21, vcc, 0, v37, vcc
	global_load_dwordx4 v[20:23], v[20:21], off
	ds_read_b128 v[24:27], v38 offset:1088
	ds_read_b128 v[28:31], v38 offset:2176
	ds_read_b128 v[32:35], v38 offset:3264
	s_waitcnt lgkmcnt(3)
	v_lshlrev_b32_e32 v39, 16, v16
	v_and_b32_e32 v16, 0xffff0000, v16
	v_lshl_add_u64 v[2:3], s[4:5], 0, v[2:3]
	v_lshl_add_u64 v[2:3], v[2:3], 0, v[146:147]
	s_cmp_eq_u32 s53, 5
	s_cselect_b64 s[4:5], -1, 0
	s_waitcnt vmcnt(3)
	v_lshlrev_b32_e32 v40, 16, v4
	v_and_b32_e32 v4, 0xffff0000, v4
	v_mul_f32_e32 v39, v39, v40
	v_mul_f32_e32 v4, v16, v4
	v_cvt_pk_bf16_f32 v4, v39, v4
	v_lshlrev_b32_e32 v16, 16, v17
	v_lshlrev_b32_e32 v39, 16, v5
	v_and_b32_e32 v17, 0xffff0000, v17
	v_and_b32_e32 v5, 0xffff0000, v5
	v_mul_f32_e32 v16, v16, v39
	v_mul_f32_e32 v5, v17, v5
	v_cvt_pk_bf16_f32 v5, v16, v5
	v_lshlrev_b32_e32 v16, 16, v18
	v_lshlrev_b32_e32 v17, 16, v6
	v_mul_f32_e32 v16, v16, v17
	v_and_b32_e32 v17, 0xffff0000, v18
	v_and_b32_e32 v6, 0xffff0000, v6
	v_mul_f32_e32 v6, v17, v6
	v_cvt_pk_bf16_f32 v6, v16, v6
	v_lshlrev_b32_e32 v16, 16, v19
	v_lshlrev_b32_e32 v17, 16, v7
	v_mul_f32_e32 v16, v16, v17
	v_and_b32_e32 v17, 0xffff0000, v19
	v_and_b32_e32 v7, 0xffff0000, v7
	v_mul_f32_e32 v7, v17, v7
	v_cvt_pk_bf16_f32 v7, v16, v7
	global_store_dwordx4 v[2:3], v[4:7], off nt
	s_waitcnt vmcnt(3)
	s_nop 0
	v_lshlrev_b32_e32 v4, 16, v8
	s_waitcnt lgkmcnt(2)
	v_lshlrev_b32_e32 v5, 16, v24
	v_mul_f32_e32 v4, v5, v4
	v_and_b32_e32 v5, 0xffff0000, v24
	v_and_b32_e32 v6, 0xffff0000, v8
	v_mul_f32_e32 v5, v5, v6
	v_cvt_pk_bf16_f32 v4, v4, v5
	v_lshlrev_b32_e32 v5, 16, v9
	v_lshlrev_b32_e32 v6, 16, v25
	v_mul_f32_e32 v5, v6, v5
	v_and_b32_e32 v6, 0xffff0000, v25
	v_and_b32_e32 v7, 0xffff0000, v9
	v_mul_f32_e32 v6, v6, v7
	v_cvt_pk_bf16_f32 v5, v5, v6
	v_lshlrev_b32_e32 v6, 16, v10
	v_lshlrev_b32_e32 v7, 16, v26
	v_mul_f32_e32 v6, v7, v6
	v_and_b32_e32 v7, 0xffff0000, v26
	v_and_b32_e32 v8, 0xffff0000, v10
	v_mul_f32_e32 v7, v7, v8
	v_cvt_pk_bf16_f32 v6, v6, v7
	v_lshlrev_b32_e32 v7, 16, v11
	v_lshlrev_b32_e32 v8, 16, v27
	v_mul_f32_e32 v7, v8, v7
	v_and_b32_e32 v8, 0xffff0000, v27
	v_and_b32_e32 v9, 0xffff0000, v11
	v_mul_f32_e32 v8, v8, v9
	v_cvt_pk_bf16_f32 v7, v7, v8
	v_add_co_u32_e32 v8, vcc, s59, v2
	s_nop 1
	v_addc_co_u32_e32 v9, vcc, 0, v3, vcc
	global_store_dwordx4 v[8:9], v[4:7], off nt
	s_waitcnt vmcnt(3)
	v_and_b32_e32 v8, 0xffff0000, v14
	v_and_b32_e32 v9, 0xffff0000, v15
	v_lshlrev_b32_e32 v4, 16, v12
	s_waitcnt lgkmcnt(1)
	v_lshlrev_b32_e32 v5, 16, v28
	v_mul_f32_e32 v4, v5, v4
	v_and_b32_e32 v5, 0xffff0000, v28
	v_and_b32_e32 v6, 0xffff0000, v12
	v_mul_f32_e32 v5, v5, v6
	v_cvt_pk_bf16_f32 v4, v4, v5
	v_lshlrev_b32_e32 v5, 16, v13
	v_lshlrev_b32_e32 v6, 16, v29
	v_mul_f32_e32 v5, v6, v5
	v_and_b32_e32 v6, 0xffff0000, v29
	v_and_b32_e32 v7, 0xffff0000, v13
	v_mul_f32_e32 v6, v6, v7
	v_cvt_pk_bf16_f32 v5, v5, v6
	v_lshlrev_b32_e32 v6, 16, v14
	v_lshlrev_b32_e32 v7, 16, v30
	v_mul_f32_e32 v6, v7, v6
	v_and_b32_e32 v7, 0xffff0000, v30
	v_mul_f32_e32 v7, v7, v8
	v_cvt_pk_bf16_f32 v6, v6, v7
	v_lshlrev_b32_e32 v7, 16, v15
	v_lshlrev_b32_e32 v8, 16, v31
	v_mul_f32_e32 v7, v8, v7
	v_and_b32_e32 v8, 0xffff0000, v31
	v_mul_f32_e32 v8, v8, v9
	v_cvt_pk_bf16_f32 v7, v7, v8
	v_add_co_u32_e32 v8, vcc, s56, v2
	s_nop 1
	v_addc_co_u32_e32 v9, vcc, 0, v3, vcc
	global_store_dwordx4 v[8:9], v[4:7], off nt
	s_waitcnt vmcnt(3)
	v_and_b32_e32 v8, 0xffff0000, v22
	v_and_b32_e32 v9, 0xffff0000, v23
	v_lshlrev_b32_e32 v4, 16, v20
	s_waitcnt lgkmcnt(0)
	v_lshlrev_b32_e32 v5, 16, v32
	v_mul_f32_e32 v4, v5, v4
	v_and_b32_e32 v5, 0xffff0000, v32
	v_and_b32_e32 v6, 0xffff0000, v20
	v_mul_f32_e32 v5, v5, v6
	v_cvt_pk_bf16_f32 v4, v4, v5
	v_lshlrev_b32_e32 v5, 16, v21
	v_lshlrev_b32_e32 v6, 16, v33
	v_mul_f32_e32 v5, v6, v5
	v_and_b32_e32 v6, 0xffff0000, v33
	v_and_b32_e32 v7, 0xffff0000, v21
	v_mul_f32_e32 v6, v6, v7
	v_cvt_pk_bf16_f32 v5, v5, v6
	v_lshlrev_b32_e32 v6, 16, v22
	v_lshlrev_b32_e32 v7, 16, v34
	v_mul_f32_e32 v6, v7, v6
	v_and_b32_e32 v7, 0xffff0000, v34
	v_mul_f32_e32 v7, v7, v8
	v_cvt_pk_bf16_f32 v6, v6, v7
	v_lshlrev_b32_e32 v7, 16, v23
	v_lshlrev_b32_e32 v8, 16, v35
	v_mul_f32_e32 v7, v8, v7
	v_and_b32_e32 v8, 0xffff0000, v35
	v_mul_f32_e32 v8, v8, v9
	v_cvt_pk_bf16_f32 v7, v7, v8
	v_add_co_u32_e32 v8, vcc, s58, v2
	s_nop 1
	v_addc_co_u32_e32 v9, vcc, 0, v3, vcc
	global_store_dwordx4 v[8:9], v[4:7], off nt
	s_nop 1
	v_add_co_u32_e32 v4, vcc, s61, v36
	s_nop 1
	v_addc_co_u32_e32 v5, vcc, 0, v37, vcc
	global_load_dwordx4 v[4:7], v[4:5], off
	v_add_co_u32_e32 v8, vcc, s62, v36
	s_nop 1
	v_addc_co_u32_e32 v9, vcc, 0, v37, vcc
	global_load_dwordx4 v[8:11], v[8:9], off
	v_add_co_u32_e32 v12, vcc, s63, v36
	s_nop 1
	v_addc_co_u32_e32 v13, vcc, 0, v37, vcc
	global_load_dwordx4 v[12:15], v[12:13], off
	v_add_co_u32_e32 v16, vcc, s64, v36
	s_waitcnt vmcnt(2)
	v_lshlrev_b32_e32 v36, 16, v4
	v_addc_co_u32_e32 v17, vcc, 0, v37, vcc
	global_load_dwordx4 v[16:19], v[16:17], off
	ds_read_b128 v[20:23], v38 offset:4352
	ds_read_b128 v[24:27], v38 offset:5440
	ds_read_b128 v[28:31], v38 offset:6528
	ds_read_b128 v[32:35], v38 offset:7616
	v_and_b32_e32 v4, 0xffff0000, v4
	s_waitcnt lgkmcnt(3)
	v_lshlrev_b32_e32 v37, 16, v20
	v_and_b32_e32 v20, 0xffff0000, v20
	v_mul_f32_e32 v36, v37, v36
	v_mul_f32_e32 v4, v20, v4
	v_cvt_pk_bf16_f32 v4, v36, v4
	v_lshlrev_b32_e32 v20, 16, v5
	v_lshlrev_b32_e32 v36, 16, v21
	v_and_b32_e32 v21, 0xffff0000, v21
	v_and_b32_e32 v5, 0xffff0000, v5
	v_mul_f32_e32 v20, v36, v20
	v_mul_f32_e32 v5, v21, v5
	v_cvt_pk_bf16_f32 v5, v20, v5
	v_lshlrev_b32_e32 v20, 16, v6
	v_lshlrev_b32_e32 v21, 16, v22
	v_mul_f32_e32 v20, v21, v20
	v_and_b32_e32 v21, 0xffff0000, v22
	v_and_b32_e32 v6, 0xffff0000, v6
	v_mul_f32_e32 v6, v21, v6
	v_cvt_pk_bf16_f32 v6, v20, v6
	v_lshlrev_b32_e32 v20, 16, v7
	v_lshlrev_b32_e32 v21, 16, v23
	v_mul_f32_e32 v20, v21, v20
	v_and_b32_e32 v21, 0xffff0000, v23
	v_and_b32_e32 v7, 0xffff0000, v7
	v_mul_f32_e32 v7, v21, v7
	v_cvt_pk_bf16_f32 v7, v20, v7
	v_add_co_u32_e32 v20, vcc, s61, v2
	s_nop 1
	v_addc_co_u32_e32 v21, vcc, 0, v3, vcc
	global_store_dwordx4 v[20:21], v[4:7], off nt
	s_waitcnt vmcnt(3)
	s_nop 0
	v_lshlrev_b32_e32 v4, 16, v8
	s_waitcnt lgkmcnt(2)
	v_lshlrev_b32_e32 v5, 16, v24
	v_mul_f32_e32 v4, v5, v4
	v_and_b32_e32 v5, 0xffff0000, v24
	v_and_b32_e32 v6, 0xffff0000, v8
	v_mul_f32_e32 v5, v5, v6
	v_cvt_pk_bf16_f32 v4, v4, v5
	v_lshlrev_b32_e32 v5, 16, v9
	v_lshlrev_b32_e32 v6, 16, v25
	v_mul_f32_e32 v5, v6, v5
	v_and_b32_e32 v6, 0xffff0000, v25
	v_and_b32_e32 v7, 0xffff0000, v9
	v_mul_f32_e32 v6, v6, v7
	v_cvt_pk_bf16_f32 v5, v5, v6
	v_lshlrev_b32_e32 v6, 16, v10
	v_lshlrev_b32_e32 v7, 16, v26
	v_mul_f32_e32 v6, v7, v6
	v_and_b32_e32 v7, 0xffff0000, v26
	v_and_b32_e32 v8, 0xffff0000, v10
	v_mul_f32_e32 v7, v7, v8
	v_cvt_pk_bf16_f32 v6, v6, v7
	v_lshlrev_b32_e32 v7, 16, v11
	v_lshlrev_b32_e32 v8, 16, v27
	v_mul_f32_e32 v7, v8, v7
	v_and_b32_e32 v8, 0xffff0000, v27
	v_and_b32_e32 v9, 0xffff0000, v11
	v_mul_f32_e32 v8, v8, v9
	v_cvt_pk_bf16_f32 v7, v7, v8
	v_add_co_u32_e32 v8, vcc, s62, v2
	s_nop 1
	v_addc_co_u32_e32 v9, vcc, 0, v3, vcc
	global_store_dwordx4 v[8:9], v[4:7], off nt
	s_waitcnt vmcnt(3)
	v_and_b32_e32 v8, 0xffff0000, v14
	v_and_b32_e32 v9, 0xffff0000, v15
	v_lshlrev_b32_e32 v4, 16, v12
	s_waitcnt lgkmcnt(1)
	v_lshlrev_b32_e32 v5, 16, v28
	v_mul_f32_e32 v4, v5, v4
	v_and_b32_e32 v5, 0xffff0000, v28
	v_and_b32_e32 v6, 0xffff0000, v12
	v_mul_f32_e32 v5, v5, v6
	v_cvt_pk_bf16_f32 v4, v4, v5
	v_lshlrev_b32_e32 v5, 16, v13
	v_lshlrev_b32_e32 v6, 16, v29
	v_mul_f32_e32 v5, v6, v5
	v_and_b32_e32 v6, 0xffff0000, v29
	v_and_b32_e32 v7, 0xffff0000, v13
	v_mul_f32_e32 v6, v6, v7
	v_cvt_pk_bf16_f32 v5, v5, v6
	v_lshlrev_b32_e32 v6, 16, v14
	v_lshlrev_b32_e32 v7, 16, v30
	v_mul_f32_e32 v6, v7, v6
	v_and_b32_e32 v7, 0xffff0000, v30
	v_mul_f32_e32 v7, v7, v8
	v_cvt_pk_bf16_f32 v6, v6, v7
	v_lshlrev_b32_e32 v7, 16, v15
	v_lshlrev_b32_e32 v8, 16, v31
	v_mul_f32_e32 v7, v8, v7
	v_and_b32_e32 v8, 0xffff0000, v31
	v_mul_f32_e32 v8, v8, v9
	v_cvt_pk_bf16_f32 v7, v7, v8
	v_add_co_u32_e32 v8, vcc, s63, v2
	s_nop 1
	v_addc_co_u32_e32 v9, vcc, 0, v3, vcc
	global_store_dwordx4 v[8:9], v[4:7], off nt
	s_waitcnt vmcnt(3)
	v_and_b32_e32 v8, 0xffff0000, v18
	v_add_co_u32_e32 v2, vcc, s64, v2
	v_lshlrev_b32_e32 v4, 16, v16
	s_waitcnt lgkmcnt(0)
	v_lshlrev_b32_e32 v5, 16, v32
	v_mul_f32_e32 v4, v5, v4
	v_and_b32_e32 v5, 0xffff0000, v32
	v_and_b32_e32 v6, 0xffff0000, v16
	v_mul_f32_e32 v5, v5, v6
	v_cvt_pk_bf16_f32 v4, v4, v5
	v_lshlrev_b32_e32 v5, 16, v17
	v_lshlrev_b32_e32 v6, 16, v33
	v_mul_f32_e32 v5, v6, v5
	v_and_b32_e32 v6, 0xffff0000, v33
	v_and_b32_e32 v7, 0xffff0000, v17
	v_mul_f32_e32 v6, v6, v7
	v_cvt_pk_bf16_f32 v5, v5, v6
	v_lshlrev_b32_e32 v6, 16, v18
	v_lshlrev_b32_e32 v7, 16, v34
	v_mul_f32_e32 v6, v7, v6
	v_and_b32_e32 v7, 0xffff0000, v34
	v_mul_f32_e32 v7, v7, v8
	v_cvt_pk_bf16_f32 v6, v6, v7
	v_lshlrev_b32_e32 v7, 16, v19
	v_lshlrev_b32_e32 v8, 16, v35
	v_mul_f32_e32 v7, v8, v7
	v_and_b32_e32 v8, 0xffff0000, v35
	v_and_b32_e32 v9, 0xffff0000, v19
	v_addc_co_u32_e32 v3, vcc, 0, v3, vcc
	v_mul_f32_e32 v8, v8, v9
	v_cvt_pk_bf16_f32 v7, v7, v8
	global_store_dwordx4 v[2:3], v[4:7], off nt
	s_barrier
	s_barrier

.LBB0_837:
	s_or_b64 exec, exec, s[6:7]
	s_waitcnt lgkmcnt(0)
	v_add_u32_e32 v74, s72, v166
	ds_read_b128 v[66:69], v74
	ds_read_b128 v[70:73], v74 offset:32
	s_lshl_b64 s[6:7], s[24:25], 13
	s_add_u32 s4, s42, s6
	s_addc_u32 s5, s43, s7
	s_lshl_b32 s24, s69, 8
	s_add_u32 s4, s4, s24
	s_addc_u32 s5, s5, 0
	s_waitcnt lgkmcnt(1)
	v_rcp_f32_e32 v75, v66
	s_add_u32 s6, s0, s6
	s_addc_u32 s7, s1, s7
	v_rcp_f32_e32 v76, v67
	v_rcp_f32_e32 v77, v68
	v_rcp_f32_e32 v78, v69
	s_waitcnt lgkmcnt(0)
	v_rcp_f32_e32 v79, v70
	ds_read_b128 v[66:69], v74 offset:64
	v_rcp_f32_e32 v80, v71
	v_rcp_f32_e32 v81, v72
	v_rcp_f32_e32 v82, v73
	ds_read_b128 v[70:73], v74 offset:96
	v_mul_u32_u24_e32 v74, 0x440, v182
	s_add_u32 s6, s6, s24
	s_mulk_i32 s70, 0x2200
	v_lshl_or_b32 v74, v163, 1, v74
	s_addc_u32 s7, s7, 0
	s_waitcnt lgkmcnt(0)
	s_barrier
	s_add_i32 s24, s70, 0
	v_mul_f32_e32 v2, v2, v75
	v_add_u32_e32 v74, s24, v74
	v_cvt_pk_bf16_f32 v2, v2, v165
	ds_write_b16 v74, v2
	v_mul_f32_e32 v2, v50, v75
	v_cvt_pk_bf16_f32 v2, v2, v165
	ds_write_b16 v74, v2 offset:64
	v_mul_f32_e32 v2, v34, v75
	v_cvt_pk_bf16_f32 v2, v2, v165
	ds_write_b16 v74, v2 offset:128
	v_mul_f32_e32 v2, v18, v75
	v_cvt_pk_bf16_f32 v2, v2, v165
	ds_write_b16 v74, v2 offset:192
	v_mul_f32_e32 v2, v3, v76
	v_cvt_pk_bf16_f32 v2, v2, v165
	ds_write_b16 v74, v2 offset:272
	v_mul_f32_e32 v2, v51, v76
	v_cvt_pk_bf16_f32 v2, v2, v165
	ds_write_b16 v74, v2 offset:336
	v_mul_f32_e32 v2, v35, v76
	v_cvt_pk_bf16_f32 v2, v2, v165
	ds_write_b16 v74, v2 offset:400
	v_mul_f32_e32 v2, v19, v76
	v_cvt_pk_bf16_f32 v2, v2, v165
	ds_write_b16 v74, v2 offset:464
	v_mul_f32_e32 v2, v4, v77
	v_cvt_pk_bf16_f32 v2, v2, v165
	ds_write_b16 v74, v2 offset:544
	v_mul_f32_e32 v2, v52, v77
	v_cvt_pk_bf16_f32 v2, v2, v165
	ds_write_b16 v74, v2 offset:608
	v_mul_f32_e32 v2, v36, v77
	v_cvt_pk_bf16_f32 v2, v2, v165
	ds_write_b16 v74, v2 offset:672
	v_mul_f32_e32 v2, v20, v77
	v_cvt_pk_bf16_f32 v2, v2, v165
	ds_write_b16 v74, v2 offset:736
	v_mul_f32_e32 v2, v5, v78
	v_cvt_pk_bf16_f32 v2, v2, v165
	ds_write_b16 v74, v2 offset:816
	v_mul_f32_e32 v2, v53, v78
	v_cvt_pk_bf16_f32 v2, v2, v165
	ds_write_b16 v74, v2 offset:880
	v_mul_f32_e32 v2, v37, v78
	v_cvt_pk_bf16_f32 v2, v2, v165
	ds_write_b16 v74, v2 offset:944
	v_mul_f32_e32 v2, v21, v78
	v_cvt_pk_bf16_f32 v2, v2, v165
	ds_write_b16 v74, v2 offset:1008
	v_mul_f32_e32 v2, v6, v79
	v_cvt_pk_bf16_f32 v2, v2, v165
	ds_write_b16 v74, v2 offset:2176
	v_mul_f32_e32 v2, v54, v79
	v_cvt_pk_bf16_f32 v2, v2, v165
	ds_write_b16 v74, v2 offset:2240
	v_mul_f32_e32 v2, v38, v79
	v_cvt_pk_bf16_f32 v2, v2, v165
	ds_write_b16 v74, v2 offset:2304
	v_mul_f32_e32 v2, v22, v79
	v_cvt_pk_bf16_f32 v2, v2, v165
	ds_write_b16 v74, v2 offset:2368
	v_mul_f32_e32 v2, v7, v80
	v_cvt_pk_bf16_f32 v2, v2, v165
	ds_write_b16 v74, v2 offset:2448
	v_mul_f32_e32 v2, v55, v80
	v_cvt_pk_bf16_f32 v2, v2, v165
	ds_write_b16 v74, v2 offset:2512
	v_mul_f32_e32 v2, v39, v80
	v_cvt_pk_bf16_f32 v2, v2, v165
	ds_write_b16 v74, v2 offset:2576
	v_mul_f32_e32 v2, v23, v80
	v_cvt_pk_bf16_f32 v2, v2, v165
	ds_write_b16 v74, v2 offset:2640
	v_mul_f32_e32 v2, v8, v81
	v_cvt_pk_bf16_f32 v2, v2, v165
	ds_write_b16 v74, v2 offset:2720
	v_mul_f32_e32 v2, v56, v81
	v_cvt_pk_bf16_f32 v2, v2, v165
	ds_write_b16 v74, v2 offset:2784
	v_mul_f32_e32 v2, v40, v81
	v_cvt_pk_bf16_f32 v2, v2, v165
	ds_write_b16 v74, v2 offset:2848
	v_mul_f32_e32 v2, v24, v81
	v_cvt_pk_bf16_f32 v2, v2, v165
	ds_write_b16 v74, v2 offset:2912
	v_mul_f32_e32 v2, v9, v82
	v_cvt_pk_bf16_f32 v2, v2, v165
	ds_write_b16 v74, v2 offset:2992
	v_mul_f32_e32 v2, v57, v82
	v_cvt_pk_bf16_f32 v2, v2, v165
	v_rcp_f32_e32 v66, v66
	ds_write_b16 v74, v2 offset:3056
	v_mul_f32_e32 v2, v41, v82
	v_cvt_pk_bf16_f32 v2, v2, v165
	ds_write_b16 v74, v2 offset:3120
	v_mul_f32_e32 v2, v25, v82
	v_cvt_pk_bf16_f32 v2, v2, v165
	ds_write_b16 v74, v2 offset:3184
	v_mul_f32_e32 v2, v10, v66
	v_cvt_pk_bf16_f32 v2, v2, v165
	ds_write_b16 v74, v2 offset:4352
	v_mul_f32_e32 v2, v58, v66
	v_cvt_pk_bf16_f32 v2, v2, v165
	v_rcp_f32_e32 v67, v67
	ds_write_b16 v74, v2 offset:4416
	v_mul_f32_e32 v2, v42, v66
	v_cvt_pk_bf16_f32 v2, v2, v165
	ds_write_b16 v74, v2 offset:4480
	v_mul_f32_e32 v2, v26, v66
	v_cvt_pk_bf16_f32 v2, v2, v165
	ds_write_b16 v74, v2 offset:4544
	v_mul_f32_e32 v2, v11, v67
	v_cvt_pk_bf16_f32 v2, v2, v165
	ds_write_b16 v74, v2 offset:4624
	v_mul_f32_e32 v2, v59, v67
	v_cvt_pk_bf16_f32 v2, v2, v165
	v_rcp_f32_e32 v68, v68
	ds_write_b16 v74, v2 offset:4688
	v_mul_f32_e32 v2, v43, v67
	v_cvt_pk_bf16_f32 v2, v2, v165
	ds_write_b16 v74, v2 offset:4752
	v_mul_f32_e32 v2, v27, v67
	v_cvt_pk_bf16_f32 v2, v2, v165
	ds_write_b16 v74, v2 offset:4816
	v_mul_f32_e32 v2, v12, v68
	v_cvt_pk_bf16_f32 v2, v2, v165
	ds_write_b16 v74, v2 offset:4896
	v_mul_f32_e32 v2, v60, v68
	v_cvt_pk_bf16_f32 v2, v2, v165
	v_rcp_f32_e32 v69, v69
	ds_write_b16 v74, v2 offset:4960
	v_mul_f32_e32 v2, v44, v68
	v_cvt_pk_bf16_f32 v2, v2, v165
	ds_write_b16 v74, v2 offset:5024
	v_mul_f32_e32 v2, v28, v68
	v_cvt_pk_bf16_f32 v2, v2, v165
	ds_write_b16 v74, v2 offset:5088
	v_mul_f32_e32 v2, v13, v69
	v_cvt_pk_bf16_f32 v2, v2, v165
	ds_write_b16 v74, v2 offset:5168
	v_mul_f32_e32 v2, v61, v69
	v_cvt_pk_bf16_f32 v2, v2, v165
	v_rcp_f32_e32 v70, v70
	ds_write_b16 v74, v2 offset:5232
	v_mul_f32_e32 v2, v45, v69
	v_cvt_pk_bf16_f32 v2, v2, v165
	ds_write_b16 v74, v2 offset:5296
	v_mul_f32_e32 v2, v29, v69
	v_cvt_pk_bf16_f32 v2, v2, v165
	ds_write_b16 v74, v2 offset:5360
	v_mul_f32_e32 v2, v14, v70
	v_cvt_pk_bf16_f32 v2, v2, v165
	ds_write_b16 v74, v2 offset:6528
	v_mul_f32_e32 v2, v62, v70
	v_cvt_pk_bf16_f32 v2, v2, v165
	v_rcp_f32_e32 v71, v71
	ds_write_b16 v74, v2 offset:6592
	v_mul_f32_e32 v2, v46, v70
	v_cvt_pk_bf16_f32 v2, v2, v165
	ds_write_b16 v74, v2 offset:6656
	v_mul_f32_e32 v2, v30, v70
	v_cvt_pk_bf16_f32 v2, v2, v165
	ds_write_b16 v74, v2 offset:6720
	v_mul_f32_e32 v2, v15, v71
	v_cvt_pk_bf16_f32 v2, v2, v165
	ds_write_b16 v74, v2 offset:6800
	v_mul_f32_e32 v2, v63, v71
	v_cvt_pk_bf16_f32 v2, v2, v165
	v_rcp_f32_e32 v72, v72
	ds_write_b16 v74, v2 offset:6864
	v_mul_f32_e32 v2, v47, v71
	v_cvt_pk_bf16_f32 v2, v2, v165
	ds_write_b16 v74, v2 offset:6928
	v_mul_f32_e32 v2, v31, v71
	v_cvt_pk_bf16_f32 v2, v2, v165
	ds_write_b16 v74, v2 offset:6992
	v_mul_f32_e32 v2, v16, v72
	v_cvt_pk_bf16_f32 v2, v2, v165
	ds_write_b16 v74, v2 offset:7072
	v_mul_f32_e32 v2, v64, v72
	v_cvt_pk_bf16_f32 v2, v2, v165
	v_rcp_f32_e32 v73, v73
	ds_write_b16 v74, v2 offset:7136
	v_mul_f32_e32 v2, v48, v72
	v_cvt_pk_bf16_f32 v2, v2, v165
	ds_write_b16 v74, v2 offset:7200
	v_mul_f32_e32 v2, v32, v72
	v_cvt_pk_bf16_f32 v2, v2, v165
	ds_write_b16 v74, v2 offset:7264
	v_mul_f32_e32 v2, v17, v73
	v_cvt_pk_bf16_f32 v2, v2, v165
	ds_write_b16 v74, v2 offset:7344
	v_mul_f32_e32 v2, v65, v73
	v_cvt_pk_bf16_f32 v2, v2, v165
	ds_write_b16 v74, v2 offset:7408
	v_mul_f32_e32 v2, v49, v73
	v_cvt_pk_bf16_f32 v2, v2, v165
	ds_write_b16 v74, v2 offset:7472
	v_mul_f32_e32 v2, v33, v73
	v_cvt_pk_bf16_f32 v2, v2, v165
	ds_write_b16 v74, v2 offset:7536
	s_waitcnt lgkmcnt(0)
	s_add_i32 s34, s34, 1
	v_ashrrev_i32_e32 v20, 4, v167
	v_add_u32_e32 v2, s68, v20
	v_ashrrev_i32_e32 v3, 31, v2
	v_lshlrev_b64 v[2:3], 13, v[2:3]
	v_lshlrev_b32_e32 v4, 4, v167
	v_and_b32_e32 v164, 0xf0, v4
	v_lshl_add_u64 v[4:5], s[6:7], 0, v[2:3]
	v_lshl_add_u64 v[36:37], v[4:5], 0, v[164:165]
	v_add_co_u32_e32 v4, vcc, s57, v36
	v_mul_lo_u32 v20, v20, s61
	s_nop 0
	v_addc_co_u32_e32 v5, vcc, 0, v37, vcc
	global_load_dwordx4 v[4:7], v[4:5], off
	v_add_co_u32_e32 v8, vcc, s58, v36
	v_add3_u32 v38, s24, v164, v20
	s_nop 0
	v_addc_co_u32_e32 v9, vcc, 0, v37, vcc
	global_load_dwordx4 v[8:11], v[8:9], off
	v_add_co_u32_e32 v12, vcc, s59, v36
	v_lshl_add_u64 v[2:3], s[4:5], 0, v[2:3]
	s_nop 0
	v_addc_co_u32_e32 v13, vcc, 0, v37, vcc
	global_load_dwordx4 v[12:15], v[12:13], off
	v_add_co_u32_e32 v16, vcc, s60, v36
	v_lshl_add_u64 v[2:3], v[2:3], 0, v[164:165]
	s_nop 0
	v_addc_co_u32_e32 v17, vcc, 0, v37, vcc
	global_load_dwordx4 v[16:19], v[16:17], off
	ds_read_b128 v[20:23], v38
	ds_read_b128 v[24:27], v38 offset:1088
	ds_read_b128 v[28:31], v38 offset:2176
	ds_read_b128 v[32:35], v38 offset:3264
	s_cmp_eq_u32 s34, 5
	s_waitcnt lgkmcnt(3)
	v_lshlrev_b32_e32 v40, 16, v20
	v_and_b32_e32 v20, 0xffff0000, v20
	s_cselect_b64 s[4:5], -1, 0
	s_waitcnt vmcnt(3)
	v_lshlrev_b32_e32 v39, 16, v4
	v_and_b32_e32 v4, 0xffff0000, v4
	v_mul_f32_e32 v39, v40, v39
	v_mul_f32_e32 v4, v20, v4
	v_cvt_pk_bf16_f32 v4, v39, v4
	v_lshlrev_b32_e32 v20, 16, v5
	v_lshlrev_b32_e32 v39, 16, v21
	v_and_b32_e32 v21, 0xffff0000, v21
	v_and_b32_e32 v5, 0xffff0000, v5
	v_mul_f32_e32 v20, v39, v20
	v_mul_f32_e32 v5, v21, v5
	v_cvt_pk_bf16_f32 v5, v20, v5
	v_lshlrev_b32_e32 v20, 16, v6
	v_lshlrev_b32_e32 v21, 16, v22
	v_mul_f32_e32 v20, v21, v20
	v_and_b32_e32 v21, 0xffff0000, v22
	v_and_b32_e32 v6, 0xffff0000, v6
	v_mul_f32_e32 v6, v21, v6
	v_cvt_pk_bf16_f32 v6, v20, v6
	v_lshlrev_b32_e32 v20, 16, v7
	v_lshlrev_b32_e32 v21, 16, v23
	v_mul_f32_e32 v20, v21, v20
	v_and_b32_e32 v21, 0xffff0000, v23
	v_and_b32_e32 v7, 0xffff0000, v7
	v_mul_f32_e32 v7, v21, v7
	v_cvt_pk_bf16_f32 v7, v20, v7
	v_add_co_u32_e32 v20, vcc, s57, v2
	s_nop 1
	v_addc_co_u32_e32 v21, vcc, 0, v3, vcc
	global_store_dwordx4 v[20:21], v[4:7], off nt
	s_waitcnt vmcnt(3)
	s_nop 0
	v_lshlrev_b32_e32 v4, 16, v8
	s_waitcnt lgkmcnt(2)
	v_lshlrev_b32_e32 v5, 16, v24
	v_mul_f32_e32 v4, v5, v4
	v_and_b32_e32 v5, 0xffff0000, v24
	v_and_b32_e32 v6, 0xffff0000, v8
	v_mul_f32_e32 v5, v5, v6
	v_cvt_pk_bf16_f32 v4, v4, v5
	v_lshlrev_b32_e32 v5, 16, v9
	v_lshlrev_b32_e32 v6, 16, v25
	v_mul_f32_e32 v5, v6, v5
	v_and_b32_e32 v6, 0xffff0000, v25
	v_and_b32_e32 v7, 0xffff0000, v9
	v_mul_f32_e32 v6, v6, v7
	v_cvt_pk_bf16_f32 v5, v5, v6
	v_lshlrev_b32_e32 v6, 16, v10
	v_lshlrev_b32_e32 v7, 16, v26
	v_mul_f32_e32 v6, v7, v6
	v_and_b32_e32 v7, 0xffff0000, v26
	v_and_b32_e32 v8, 0xffff0000, v10
	v_mul_f32_e32 v7, v7, v8
	v_cvt_pk_bf16_f32 v6, v6, v7
	v_lshlrev_b32_e32 v7, 16, v11
	v_lshlrev_b32_e32 v8, 16, v27
	v_mul_f32_e32 v7, v8, v7
	v_and_b32_e32 v8, 0xffff0000, v27
	v_and_b32_e32 v9, 0xffff0000, v11
	v_mul_f32_e32 v8, v8, v9
	v_cvt_pk_bf16_f32 v7, v7, v8
	v_add_co_u32_e32 v8, vcc, s58, v2
	s_nop 1
	v_addc_co_u32_e32 v9, vcc, 0, v3, vcc
	global_store_dwordx4 v[8:9], v[4:7], off nt
	s_waitcnt vmcnt(3)
	v_and_b32_e32 v8, 0xffff0000, v14
	v_and_b32_e32 v9, 0xffff0000, v15
	v_lshlrev_b32_e32 v4, 16, v12
	s_waitcnt lgkmcnt(1)
	v_lshlrev_b32_e32 v5, 16, v28
	v_mul_f32_e32 v4, v5, v4
	v_and_b32_e32 v5, 0xffff0000, v28
	v_and_b32_e32 v6, 0xffff0000, v12
	v_mul_f32_e32 v5, v5, v6
	v_cvt_pk_bf16_f32 v4, v4, v5
	v_lshlrev_b32_e32 v5, 16, v13
	v_lshlrev_b32_e32 v6, 16, v29
	v_mul_f32_e32 v5, v6, v5
	v_and_b32_e32 v6, 0xffff0000, v29
	v_and_b32_e32 v7, 0xffff0000, v13
	v_mul_f32_e32 v6, v6, v7
	v_cvt_pk_bf16_f32 v5, v5, v6
	v_lshlrev_b32_e32 v6, 16, v14
	v_lshlrev_b32_e32 v7, 16, v30
	v_mul_f32_e32 v6, v7, v6
	v_and_b32_e32 v7, 0xffff0000, v30
	v_mul_f32_e32 v7, v7, v8
	v_cvt_pk_bf16_f32 v6, v6, v7
	v_lshlrev_b32_e32 v7, 16, v15
	v_lshlrev_b32_e32 v8, 16, v31
	v_mul_f32_e32 v7, v8, v7
	v_and_b32_e32 v8, 0xffff0000, v31
	v_mul_f32_e32 v8, v8, v9
	v_cvt_pk_bf16_f32 v7, v7, v8
	v_add_co_u32_e32 v8, vcc, s59, v2
	s_nop 1
	v_addc_co_u32_e32 v9, vcc, 0, v3, vcc
	global_store_dwordx4 v[8:9], v[4:7], off nt
	s_waitcnt vmcnt(3)
	v_and_b32_e32 v8, 0xffff0000, v18
	v_and_b32_e32 v9, 0xffff0000, v19
	v_lshlrev_b32_e32 v4, 16, v16
	s_waitcnt lgkmcnt(0)
	v_lshlrev_b32_e32 v5, 16, v32
	v_mul_f32_e32 v4, v5, v4
	v_and_b32_e32 v5, 0xffff0000, v32
	v_and_b32_e32 v6, 0xffff0000, v16
	v_mul_f32_e32 v5, v5, v6
	v_cvt_pk_bf16_f32 v4, v4, v5
	v_lshlrev_b32_e32 v5, 16, v17
	v_lshlrev_b32_e32 v6, 16, v33
	v_mul_f32_e32 v5, v6, v5
	v_and_b32_e32 v6, 0xffff0000, v33
	v_and_b32_e32 v7, 0xffff0000, v17
	v_mul_f32_e32 v6, v6, v7
	v_cvt_pk_bf16_f32 v5, v5, v6
	v_lshlrev_b32_e32 v6, 16, v18
	v_lshlrev_b32_e32 v7, 16, v34
	v_mul_f32_e32 v6, v7, v6
	v_and_b32_e32 v7, 0xffff0000, v34
	v_mul_f32_e32 v7, v7, v8
	v_cvt_pk_bf16_f32 v6, v6, v7
	v_lshlrev_b32_e32 v7, 16, v19
	v_lshlrev_b32_e32 v8, 16, v35
	v_mul_f32_e32 v7, v8, v7
	v_and_b32_e32 v8, 0xffff0000, v35
	v_mul_f32_e32 v8, v8, v9
	v_cvt_pk_bf16_f32 v7, v7, v8
	v_add_co_u32_e32 v8, vcc, s60, v2
	s_nop 1
	v_addc_co_u32_e32 v9, vcc, 0, v3, vcc
	global_store_dwordx4 v[8:9], v[4:7], off nt
	s_nop 1
	v_add_co_u32_e32 v4, vcc, s62, v36
	s_nop 1
	v_addc_co_u32_e32 v5, vcc, 0, v37, vcc
	global_load_dwordx4 v[4:7], v[4:5], off
	v_add_co_u32_e32 v8, vcc, s63, v36
	s_nop 1
	v_addc_co_u32_e32 v9, vcc, 0, v37, vcc
	global_load_dwordx4 v[8:11], v[8:9], off
	v_add_co_u32_e32 v12, vcc, s64, v36
	s_nop 1
	v_addc_co_u32_e32 v13, vcc, 0, v37, vcc
	global_load_dwordx4 v[12:15], v[12:13], off
	v_add_co_u32_e32 v16, vcc, s65, v36
	s_waitcnt vmcnt(2)
	v_lshlrev_b32_e32 v36, 16, v4
	v_addc_co_u32_e32 v17, vcc, 0, v37, vcc
	global_load_dwordx4 v[16:19], v[16:17], off
	ds_read_b128 v[20:23], v38 offset:4352
	ds_read_b128 v[24:27], v38 offset:5440
	ds_read_b128 v[28:31], v38 offset:6528
	ds_read_b128 v[32:35], v38 offset:7616
	v_and_b32_e32 v4, 0xffff0000, v4
	s_waitcnt lgkmcnt(3)
	v_lshlrev_b32_e32 v37, 16, v20
	v_and_b32_e32 v20, 0xffff0000, v20
	v_mul_f32_e32 v36, v37, v36
	v_mul_f32_e32 v4, v20, v4
	v_cvt_pk_bf16_f32 v4, v36, v4
	v_lshlrev_b32_e32 v20, 16, v5
	v_lshlrev_b32_e32 v36, 16, v21
	v_and_b32_e32 v21, 0xffff0000, v21
	v_and_b32_e32 v5, 0xffff0000, v5
	v_mul_f32_e32 v20, v36, v20
	v_mul_f32_e32 v5, v21, v5
	v_cvt_pk_bf16_f32 v5, v20, v5
	v_lshlrev_b32_e32 v20, 16, v6
	v_lshlrev_b32_e32 v21, 16, v22
	v_mul_f32_e32 v20, v21, v20
	v_and_b32_e32 v21, 0xffff0000, v22
	v_and_b32_e32 v6, 0xffff0000, v6
	v_mul_f32_e32 v6, v21, v6
	v_cvt_pk_bf16_f32 v6, v20, v6
	v_lshlrev_b32_e32 v20, 16, v7
	v_lshlrev_b32_e32 v21, 16, v23
	v_mul_f32_e32 v20, v21, v20
	v_and_b32_e32 v21, 0xffff0000, v23
	v_and_b32_e32 v7, 0xffff0000, v7
	v_mul_f32_e32 v7, v21, v7
	v_cvt_pk_bf16_f32 v7, v20, v7
	v_add_co_u32_e32 v20, vcc, s62, v2
	s_nop 1
	v_addc_co_u32_e32 v21, vcc, 0, v3, vcc
	global_store_dwordx4 v[20:21], v[4:7], off nt
	s_waitcnt vmcnt(3)
	s_nop 0
	v_lshlrev_b32_e32 v4, 16, v8
	s_waitcnt lgkmcnt(2)
	v_lshlrev_b32_e32 v5, 16, v24
	v_mul_f32_e32 v4, v5, v4
	v_and_b32_e32 v5, 0xffff0000, v24
	v_and_b32_e32 v6, 0xffff0000, v8
	v_mul_f32_e32 v5, v5, v6
	v_cvt_pk_bf16_f32 v4, v4, v5
	v_lshlrev_b32_e32 v5, 16, v9
	v_lshlrev_b32_e32 v6, 16, v25
	v_mul_f32_e32 v5, v6, v5
	v_and_b32_e32 v6, 0xffff0000, v25
	v_and_b32_e32 v7, 0xffff0000, v9
	v_mul_f32_e32 v6, v6, v7
	v_cvt_pk_bf16_f32 v5, v5, v6
	v_lshlrev_b32_e32 v6, 16, v10
	v_lshlrev_b32_e32 v7, 16, v26
	v_mul_f32_e32 v6, v7, v6
	v_and_b32_e32 v7, 0xffff0000, v26
	v_and_b32_e32 v8, 0xffff0000, v10
	v_mul_f32_e32 v7, v7, v8
	v_cvt_pk_bf16_f32 v6, v6, v7
	v_lshlrev_b32_e32 v7, 16, v11
	v_lshlrev_b32_e32 v8, 16, v27
	v_mul_f32_e32 v7, v8, v7
	v_and_b32_e32 v8, 0xffff0000, v27
	v_and_b32_e32 v9, 0xffff0000, v11
	v_mul_f32_e32 v8, v8, v9
	v_cvt_pk_bf16_f32 v7, v7, v8
	v_add_co_u32_e32 v8, vcc, s63, v2
	s_nop 1
	v_addc_co_u32_e32 v9, vcc, 0, v3, vcc
	global_store_dwordx4 v[8:9], v[4:7], off nt
	s_waitcnt vmcnt(3)
	v_and_b32_e32 v8, 0xffff0000, v14
	v_and_b32_e32 v9, 0xffff0000, v15
	v_lshlrev_b32_e32 v4, 16, v12
	s_waitcnt lgkmcnt(1)
	v_lshlrev_b32_e32 v5, 16, v28
	v_mul_f32_e32 v4, v5, v4
	v_and_b32_e32 v5, 0xffff0000, v28
	v_and_b32_e32 v6, 0xffff0000, v12
	v_mul_f32_e32 v5, v5, v6
	v_cvt_pk_bf16_f32 v4, v4, v5
	v_lshlrev_b32_e32 v5, 16, v13
	v_lshlrev_b32_e32 v6, 16, v29
	v_mul_f32_e32 v5, v6, v5
	v_and_b32_e32 v6, 0xffff0000, v29
	v_and_b32_e32 v7, 0xffff0000, v13
	v_mul_f32_e32 v6, v6, v7
	v_cvt_pk_bf16_f32 v5, v5, v6
	v_lshlrev_b32_e32 v6, 16, v14
	v_lshlrev_b32_e32 v7, 16, v30
	v_mul_f32_e32 v6, v7, v6
	v_and_b32_e32 v7, 0xffff0000, v30
	v_mul_f32_e32 v7, v7, v8
	v_cvt_pk_bf16_f32 v6, v6, v7
	v_lshlrev_b32_e32 v7, 16, v15
	v_lshlrev_b32_e32 v8, 16, v31
	v_mul_f32_e32 v7, v8, v7
	v_and_b32_e32 v8, 0xffff0000, v31
	v_mul_f32_e32 v8, v8, v9
	v_cvt_pk_bf16_f32 v7, v7, v8
	v_add_co_u32_e32 v8, vcc, s64, v2
	s_nop 1
	v_addc_co_u32_e32 v9, vcc, 0, v3, vcc
	global_store_dwordx4 v[8:9], v[4:7], off nt
	s_waitcnt vmcnt(3)
	v_and_b32_e32 v8, 0xffff0000, v18
	v_add_co_u32_e32 v2, vcc, s65, v2
	v_lshlrev_b32_e32 v4, 16, v16
	s_waitcnt lgkmcnt(0)
	v_lshlrev_b32_e32 v5, 16, v32
	v_mul_f32_e32 v4, v5, v4
	v_and_b32_e32 v5, 0xffff0000, v32
	v_and_b32_e32 v6, 0xffff0000, v16
	v_mul_f32_e32 v5, v5, v6
	v_cvt_pk_bf16_f32 v4, v4, v5
	v_lshlrev_b32_e32 v5, 16, v17
	v_lshlrev_b32_e32 v6, 16, v33
	v_mul_f32_e32 v5, v6, v5
	v_and_b32_e32 v6, 0xffff0000, v33
	v_and_b32_e32 v7, 0xffff0000, v17
	v_mul_f32_e32 v6, v6, v7
	v_cvt_pk_bf16_f32 v5, v5, v6
	v_lshlrev_b32_e32 v6, 16, v18
	v_lshlrev_b32_e32 v7, 16, v34
	v_mul_f32_e32 v6, v7, v6
	v_and_b32_e32 v7, 0xffff0000, v34
	v_mul_f32_e32 v7, v7, v8
	v_cvt_pk_bf16_f32 v6, v6, v7
	v_lshlrev_b32_e32 v7, 16, v19
	v_lshlrev_b32_e32 v8, 16, v35
	v_mul_f32_e32 v7, v8, v7
	v_and_b32_e32 v8, 0xffff0000, v35
	v_and_b32_e32 v9, 0xffff0000, v19
	v_addc_co_u32_e32 v3, vcc, 0, v3, vcc
	v_mul_f32_e32 v8, v8, v9
	v_cvt_pk_bf16_f32 v7, v7, v8
	global_store_dwordx4 v[2:3], v[4:7], off nt
	s_barrier
	s_barrier

.LBB0_951:
	s_mul_i32 s15, s28, 0x3000
	s_mul_hi_i32 s17, s28, 0x3000
	s_and_b64 s[24:25], s[24:25], exec
	s_cselect_b32 s29, s17, 0
	s_cselect_b32 s28, s15, 0x6000
	s_lshl_b64 s[34:35], s[34:35], 14
	s_add_u32 s24, s30, s34
	s_addc_u32 s25, s31, s35
	s_lshl_b64 s[28:29], s[28:29], 2
	v_lshl_or_b32 v176, s62, 8, v163
	s_add_u32 s28, s20, s28
	v_ashrrev_i32_e32 v177, 31, v176
	s_addc_u32 s29, s21, s29
	v_lshl_add_u64 v[134:135], v[150:151], 0, v[176:177]
	v_lshl_add_u64 v[130:131], v[176:177], 2, s[28:29]
	v_lshlrev_b64 v[186:187], 2, v[134:135]
	v_add_co_u32_e32 v132, vcc, s58, v130
	v_lshl_add_u64 v[188:189], s[24:25], 0, v[186:187]
	s_nop 0
	v_addc_co_u32_e32 v133, vcc, 0, v131, vcc
	global_load_dwordx4 v[182:185], v[188:189], off nt
	global_load_dwordx4 v[142:145], v[132:133], off nt
	s_add_u32 s26, s26, s34
	s_addc_u32 s27, s27, s35
	v_lshl_add_u64 v[130:131], v[130:131], 0, s[12:13]
	v_lshl_add_u64 v[186:187], s[26:27], 0, v[186:187]
	global_load_dwordx4 v[138:141], v[130:131], off offset:64 nt
	global_load_dwordx4 v[134:137], v[130:131], off offset:512 nt
	s_nop 0
	global_load_dwordx4 v[130:133], v[130:131], off offset:576 nt
	s_andn2_b64 vcc, exec, s[0:1]
	s_mov_b64 s[0:1], -1
	s_waitcnt vmcnt(0)
	v_pk_fma_f32 v[128:129], v[128:129], v[144:145], v[184:185]
	v_pk_fma_f32 v[126:127], v[126:127], v[142:143], v[182:183]
	global_store_dwordx4 v[186:187], v[126:129], off nt
	global_load_dwordx4 v[126:129], v[188:189], off offset:64 nt
	s_waitcnt vmcnt(0)
	v_pk_fma_f32 v[124:125], v[124:125], v[140:141], v[128:129]
	v_pk_fma_f32 v[122:123], v[122:123], v[138:139], v[126:127]
	global_store_dwordx4 v[186:187], v[122:125], off offset:64 nt
	global_load_dwordx4 v[122:125], v[188:189], off offset:512 nt
	s_waitcnt vmcnt(0)
	v_pk_fma_f32 v[120:121], v[120:121], v[136:137], v[124:125]
	v_pk_fma_f32 v[118:119], v[118:119], v[134:135], v[122:123]
	global_store_dwordx4 v[186:187], v[118:121], off offset:512 nt
	global_load_dwordx4 v[118:121], v[188:189], off offset:576 nt
	v_lshl_add_u64 v[122:123], v[152:153], 0, v[176:177]
	v_lshlrev_b64 v[122:123], 2, v[122:123]
	v_lshl_add_u64 v[124:125], s[24:25], 0, v[122:123]
	s_waitcnt vmcnt(0)
	v_pk_fma_f32 v[108:109], v[108:109], v[132:133], v[120:121]
	v_pk_fma_f32 v[106:107], v[106:107], v[130:131], v[118:119]
	global_store_dwordx4 v[186:187], v[106:109], off offset:576 nt
	global_load_dwordx4 v[106:109], v[124:125], off nt
	v_lshl_add_u64 v[118:119], s[26:27], 0, v[122:123]
	s_waitcnt vmcnt(0)
	v_pk_fma_f32 v[108:109], v[116:117], v[144:145], v[108:109]
	v_pk_fma_f32 v[106:107], v[114:115], v[142:143], v[106:107]
	global_store_dwordx4 v[118:119], v[106:109], off nt
	global_load_dwordx4 v[106:109], v[124:125], off offset:64 nt
	s_waitcnt vmcnt(0)
	v_pk_fma_f32 v[108:109], v[112:113], v[140:141], v[108:109]
	v_pk_fma_f32 v[106:107], v[110:111], v[138:139], v[106:107]
	global_store_dwordx4 v[118:119], v[106:109], off offset:64 nt
	global_load_dwordx4 v[106:109], v[124:125], off offset:512 nt
	s_waitcnt vmcnt(0)
	v_pk_fma_f32 v[104:105], v[104:105], v[136:137], v[108:109]
	v_pk_fma_f32 v[102:103], v[102:103], v[134:135], v[106:107]
	global_store_dwordx4 v[118:119], v[102:105], off offset:512 nt
	global_load_dwordx4 v[102:105], v[124:125], off offset:576 nt
	v_lshl_add_u64 v[106:107], v[154:155], 0, v[176:177]
	v_lshlrev_b64 v[106:107], 2, v[106:107]
	v_lshl_add_u64 v[108:109], s[24:25], 0, v[106:107]
	s_waitcnt vmcnt(0)
	v_pk_fma_f32 v[92:93], v[92:93], v[132:133], v[104:105]
	v_pk_fma_f32 v[90:91], v[90:91], v[130:131], v[102:103]
	global_store_dwordx4 v[118:119], v[90:93], off offset:576 nt
	global_load_dwordx4 v[90:93], v[108:109], off nt
	v_lshl_add_u64 v[102:103], s[26:27], 0, v[106:107]
	s_waitcnt vmcnt(0)
	v_pk_fma_f32 v[92:93], v[100:101], v[144:145], v[92:93]
	v_pk_fma_f32 v[90:91], v[98:99], v[142:143], v[90:91]
	global_store_dwordx4 v[102:103], v[90:93], off nt
	global_load_dwordx4 v[90:93], v[108:109], off offset:64 nt
	s_waitcnt vmcnt(0)
	v_pk_fma_f32 v[92:93], v[96:97], v[140:141], v[92:93]
	v_pk_fma_f32 v[90:91], v[94:95], v[138:139], v[90:91]
	global_store_dwordx4 v[102:103], v[90:93], off offset:64 nt
	global_load_dwordx4 v[90:93], v[108:109], off offset:512 nt
	s_waitcnt vmcnt(0)
	v_pk_fma_f32 v[88:89], v[88:89], v[136:137], v[92:93]
	v_pk_fma_f32 v[86:87], v[86:87], v[134:135], v[90:91]
	global_store_dwordx4 v[102:103], v[86:89], off offset:512 nt
	global_load_dwordx4 v[86:89], v[108:109], off offset:576 nt
	v_lshl_add_u64 v[90:91], v[156:157], 0, v[176:177]
	v_lshlrev_b64 v[90:91], 2, v[90:91]
	v_lshl_add_u64 v[92:93], s[24:25], 0, v[90:91]
	s_waitcnt vmcnt(0)
	v_pk_fma_f32 v[76:77], v[76:77], v[132:133], v[88:89]
	v_pk_fma_f32 v[74:75], v[74:75], v[130:131], v[86:87]
	global_store_dwordx4 v[102:103], v[74:77], off offset:576 nt
	global_load_dwordx4 v[74:77], v[92:93], off nt
	v_lshl_add_u64 v[86:87], s[26:27], 0, v[90:91]
	s_waitcnt vmcnt(0)
	v_pk_fma_f32 v[76:77], v[84:85], v[144:145], v[76:77]
	v_pk_fma_f32 v[74:75], v[82:83], v[142:143], v[74:75]
	global_store_dwordx4 v[86:87], v[74:77], off nt
	global_load_dwordx4 v[74:77], v[92:93], off offset:64 nt
	s_waitcnt vmcnt(0)
	v_pk_fma_f32 v[76:77], v[80:81], v[140:141], v[76:77]
	v_pk_fma_f32 v[74:75], v[78:79], v[138:139], v[74:75]
	global_store_dwordx4 v[86:87], v[74:77], off offset:64 nt
	global_load_dwordx4 v[74:77], v[92:93], off offset:512 nt
	s_waitcnt vmcnt(0)
	v_pk_fma_f32 v[72:73], v[72:73], v[136:137], v[76:77]
	v_pk_fma_f32 v[70:71], v[70:71], v[134:135], v[74:75]
	global_store_dwordx4 v[86:87], v[70:73], off offset:512 nt
	global_load_dwordx4 v[70:73], v[92:93], off offset:576 nt
	v_lshl_add_u64 v[74:75], v[158:159], 0, v[176:177]
	v_lshlrev_b64 v[74:75], 2, v[74:75]
	v_lshl_add_u64 v[76:77], s[24:25], 0, v[74:75]
	s_waitcnt vmcnt(0)
	v_pk_fma_f32 v[68:69], v[68:69], v[132:133], v[72:73]
	v_pk_fma_f32 v[66:67], v[66:67], v[130:131], v[70:71]
	global_store_dwordx4 v[86:87], v[66:69], off offset:576 nt
	global_load_dwordx4 v[66:69], v[76:77], off nt
	v_lshl_add_u64 v[70:71], s[26:27], 0, v[74:75]
	s_waitcnt vmcnt(0)
	v_pk_fma_f32 v[64:65], v[64:65], v[144:145], v[68:69]
	v_pk_fma_f32 v[62:63], v[62:63], v[142:143], v[66:67]
	global_store_dwordx4 v[70:71], v[62:65], off nt
	global_load_dwordx4 v[62:65], v[76:77], off offset:64 nt
	s_waitcnt vmcnt(0)
	v_pk_fma_f32 v[60:61], v[60:61], v[140:141], v[64:65]
	v_pk_fma_f32 v[58:59], v[58:59], v[138:139], v[62:63]
	global_store_dwordx4 v[70:71], v[58:61], off offset:64 nt
	global_load_dwordx4 v[58:61], v[76:77], off offset:512 nt
	s_waitcnt vmcnt(0)
	v_pk_fma_f32 v[56:57], v[56:57], v[136:137], v[60:61]
	v_pk_fma_f32 v[54:55], v[54:55], v[134:135], v[58:59]
	global_store_dwordx4 v[70:71], v[54:57], off offset:512 nt
	global_load_dwordx4 v[54:57], v[76:77], off offset:576 nt
	v_lshl_add_u64 v[58:59], v[160:161], 0, v[176:177]
	v_lshlrev_b64 v[58:59], 2, v[58:59]
	v_lshl_add_u64 v[60:61], s[24:25], 0, v[58:59]
	s_waitcnt vmcnt(0)
	v_pk_fma_f32 v[44:45], v[44:45], v[132:133], v[56:57]
	v_pk_fma_f32 v[42:43], v[42:43], v[130:131], v[54:55]
	global_store_dwordx4 v[70:71], v[42:45], off offset:576 nt
	global_load_dwordx4 v[42:45], v[60:61], off nt
	v_lshl_add_u64 v[54:55], s[26:27], 0, v[58:59]
	s_waitcnt vmcnt(0)
	v_pk_fma_f32 v[44:45], v[52:53], v[144:145], v[44:45]
	v_pk_fma_f32 v[42:43], v[50:51], v[142:143], v[42:43]
	global_store_dwordx4 v[54:55], v[42:45], off nt
	global_load_dwordx4 v[42:45], v[60:61], off offset:64 nt
	s_waitcnt vmcnt(0)
	v_pk_fma_f32 v[44:45], v[48:49], v[140:141], v[44:45]
	v_pk_fma_f32 v[42:43], v[46:47], v[138:139], v[42:43]
	global_store_dwordx4 v[54:55], v[42:45], off offset:64 nt
	global_load_dwordx4 v[42:45], v[60:61], off offset:512 nt
	s_waitcnt vmcnt(0)
	v_pk_fma_f32 v[40:41], v[40:41], v[136:137], v[44:45]
	v_pk_fma_f32 v[38:39], v[38:39], v[134:135], v[42:43]
	global_store_dwordx4 v[54:55], v[38:41], off offset:512 nt
	global_load_dwordx4 v[38:41], v[60:61], off offset:576 nt
	v_lshl_add_u64 v[42:43], v[164:165], 0, v[176:177]
	v_lshlrev_b64 v[42:43], 2, v[42:43]
	v_lshl_add_u64 v[44:45], s[24:25], 0, v[42:43]
	s_waitcnt vmcnt(0)
	v_pk_fma_f32 v[28:29], v[28:29], v[132:133], v[40:41]
	v_pk_fma_f32 v[26:27], v[26:27], v[130:131], v[38:39]
	global_store_dwordx4 v[54:55], v[26:29], off offset:576 nt
	global_load_dwordx4 v[26:29], v[44:45], off nt
	v_lshl_add_u64 v[38:39], s[26:27], 0, v[42:43]
	s_waitcnt vmcnt(0)
	v_pk_fma_f32 v[28:29], v[36:37], v[144:145], v[28:29]
	v_pk_fma_f32 v[26:27], v[34:35], v[142:143], v[26:27]
	global_store_dwordx4 v[38:39], v[26:29], off nt
	global_load_dwordx4 v[26:29], v[44:45], off offset:64 nt
	s_waitcnt vmcnt(0)
	v_pk_fma_f32 v[28:29], v[32:33], v[140:141], v[28:29]
	v_pk_fma_f32 v[26:27], v[30:31], v[138:139], v[26:27]
	global_store_dwordx4 v[38:39], v[26:29], off offset:64 nt
	global_load_dwordx4 v[26:29], v[44:45], off offset:512 nt
	s_waitcnt vmcnt(0)
	v_pk_fma_f32 v[24:25], v[24:25], v[136:137], v[28:29]
	v_pk_fma_f32 v[22:23], v[22:23], v[134:135], v[26:27]
	global_store_dwordx4 v[38:39], v[22:25], off offset:512 nt
	global_load_dwordx4 v[22:25], v[44:45], off offset:576 nt
	v_lshl_add_u64 v[26:27], v[166:167], 0, v[176:177]
	v_lshlrev_b64 v[26:27], 2, v[26:27]
	v_lshl_add_u64 v[28:29], s[24:25], 0, v[26:27]
	s_waitcnt vmcnt(0)
	v_pk_fma_f32 v[12:13], v[12:13], v[132:133], v[24:25]
	v_pk_fma_f32 v[10:11], v[10:11], v[130:131], v[22:23]
	global_store_dwordx4 v[38:39], v[10:13], off offset:576 nt
	global_load_dwordx4 v[10:13], v[28:29], off nt
	v_lshl_add_u64 v[22:23], s[26:27], 0, v[26:27]
	s_waitcnt vmcnt(0)
	v_pk_fma_f32 v[12:13], v[20:21], v[144:145], v[12:13]
	v_pk_fma_f32 v[10:11], v[18:19], v[142:143], v[10:11]
	global_store_dwordx4 v[22:23], v[10:13], off nt
	global_load_dwordx4 v[10:13], v[28:29], off offset:64 nt
	s_waitcnt vmcnt(0)
	v_pk_fma_f32 v[12:13], v[16:17], v[140:141], v[12:13]
	v_pk_fma_f32 v[10:11], v[14:15], v[138:139], v[10:11]
	global_store_dwordx4 v[22:23], v[10:13], off offset:64 nt
	global_load_dwordx4 v[10:13], v[28:29], off offset:512 nt
	s_waitcnt vmcnt(0)
	v_pk_fma_f32 v[8:9], v[8:9], v[136:137], v[12:13]
	v_pk_fma_f32 v[6:7], v[6:7], v[134:135], v[10:11]
	global_store_dwordx4 v[22:23], v[6:9], off offset:512 nt
	global_load_dwordx4 v[6:9], v[28:29], off offset:576 nt
	s_waitcnt vmcnt(0)
	v_pk_fma_f32 v[4:5], v[4:5], v[132:133], v[8:9]
	v_pk_fma_f32 v[2:3], v[2:3], v[130:131], v[6:7]
	global_store_dwordx4 v[22:23], v[2:5], off offset:576 nt
	s_cbranch_vccnz .LBB0_940
	s_andn2_b64 vcc, exec, s[6:7]
	s_cbranch_vccnz .LBB0_939
	s_barrier
	s_branch .LBB0_939

.LBB0_957:
	s_or_b64 exec, exec, s[0:1]
	s_waitcnt vmcnt(0)
	v_mul_f32_e32 v6, v51, v53
	ds_write2_b32 v2, v52, v6 offset0:172 offset1:238
	s_waitcnt lgkmcnt(0)
	ds_read2_b32 v[6:7], v41 offset1:33
	s_waitcnt lgkmcnt(0)
	v_cvt_pk_bf16_f32 v52, v6, v7
	ds_read2_b32 v[6:7], v41 offset0:66 offset1:99
	v_add_u32_e32 v56, s16, v40
	s_waitcnt lgkmcnt(0)
	v_cvt_pk_bf16_f32 v53, v6, v7
	ds_read2_b32 v[6:7], v41 offset0:132 offset1:165
	s_ashr_i32 s7, s6, 31
	v_ashrrev_i32_e32 v57, 31, v56
	s_waitcnt lgkmcnt(0)
	v_cvt_pk_bf16_f32 v54, v6, v7
	ds_read2_b32 v[6:7], v41 offset0:198 offset1:231
	v_lshl_add_u64 v[58:59], s[6:7], 1, v[4:5]
	v_lshlrev_b64 v[60:61], 13, v[56:57]
	s_waitcnt lgkmcnt(0)
	v_cvt_pk_bf16_f32 v55, v6, v7
	ds_read2_b32 v[6:7], v41 offset0:8 offset1:41
	v_lshl_add_u64 v[60:61], v[58:59], 0, v[60:61]
	global_store_dwordx4 v[60:61], v[52:55], off nt
	v_add_u32_e32 v60, 8, v56
	v_ashrrev_i32_e32 v61, 31, v60
	s_waitcnt lgkmcnt(0)
	v_cvt_pk_bf16_f32 v52, v6, v7
	ds_read2_b32 v[6:7], v41 offset0:74 offset1:107
	s_waitcnt lgkmcnt(0)
	v_cvt_pk_bf16_f32 v53, v6, v7
	ds_read2_b32 v[6:7], v41 offset0:140 offset1:173
	s_waitcnt lgkmcnt(0)
	v_cvt_pk_bf16_f32 v54, v6, v7
	ds_read2_b32 v[6:7], v41 offset0:206 offset1:239
	v_lshlrev_b64 v[60:61], 13, v[60:61]
	s_waitcnt lgkmcnt(0)
	v_cvt_pk_bf16_f32 v55, v6, v7
	ds_read2_b32 v[6:7], v41 offset0:16 offset1:49
	v_lshl_add_u64 v[60:61], v[58:59], 0, v[60:61]
	global_store_dwordx4 v[60:61], v[52:55], off nt
	v_add_u32_e32 v60, 16, v56
	v_ashrrev_i32_e32 v61, 31, v60
	s_waitcnt lgkmcnt(0)
	v_cvt_pk_bf16_f32 v52, v6, v7
	ds_read2_b32 v[6:7], v41 offset0:82 offset1:115
	s_waitcnt lgkmcnt(0)
	v_cvt_pk_bf16_f32 v53, v6, v7
	ds_read2_b32 v[6:7], v41 offset0:148 offset1:181
	s_waitcnt lgkmcnt(0)
	v_cvt_pk_bf16_f32 v54, v6, v7
	ds_read2_b32 v[6:7], v41 offset0:214 offset1:247
	v_lshlrev_b64 v[60:61], 13, v[60:61]
	v_add_u32_e32 v56, 24, v56
	s_waitcnt lgkmcnt(0)
	v_cvt_pk_bf16_f32 v55, v6, v7
	ds_read2_b32 v[6:7], v41 offset0:24 offset1:57
	v_lshl_add_u64 v[60:61], v[58:59], 0, v[60:61]
	v_ashrrev_i32_e32 v57, 31, v56
	global_store_dwordx4 v[60:61], v[52:55], off nt
	v_lshlrev_b64 v[56:57], 13, v[56:57]
	v_lshl_add_u64 v[56:57], v[58:59], 0, v[56:57]
	s_waitcnt lgkmcnt(0)
	v_cvt_pk_bf16_f32 v52, v6, v7
	ds_read2_b32 v[6:7], v41 offset0:90 offset1:123
	s_waitcnt lgkmcnt(0)
	v_cvt_pk_bf16_f32 v53, v6, v7
	ds_read2_b32 v[6:7], v41 offset0:156 offset1:189
	s_waitcnt lgkmcnt(0)
	v_cvt_pk_bf16_f32 v54, v6, v7
	ds_read2_b32 v[6:7], v41 offset0:222 offset1:255
	s_waitcnt lgkmcnt(0)
	v_cvt_pk_bf16_f32 v55, v6, v7
	global_store_dwordx4 v[56:57], v[52:55], off nt
	s_waitcnt lgkmcnt(0)
	s_add_i32 s10, s10, s11
	s_add_i32 s12, s12, s13
	s_cmpk_lt_i32 s10, 0x5a00
	s_cbranch_scc0 .LBB0_1000

.LBB0_1731:
	s_mul_i32 s15, s24, 0x3000
	s_mul_hi_i32 s17, s24, 0x3000
	s_and_b64 s[22:23], s[22:23], exec
	s_cselect_b32 s25, s17, 0
	s_cselect_b32 s24, s15, 0x6000
	s_lshl_b64 s[22:23], s[28:29], 14
	s_add_u32 s22, s26, s22
	s_addc_u32 s23, s27, s23
	s_lshl_b64 s[24:25], s[24:25], 2
	v_lshl_or_b32 v130, s51, 8, v163
	s_add_u32 s24, s96, s24
	v_ashrrev_i32_e32 v131, 31, v130
	s_addc_u32 s25, s97, s25
	v_lshlrev_b64 v[176:177], 2, v[130:131]
	v_lshl_add_u64 v[130:131], s[24:25], 0, v[176:177]
	v_lshl_add_u64 v[142:143], v[130:131], 0, s[12:13]
	v_add_co_u32_e32 v130, vcc, s47, v130
	v_lshl_add_u64 v[134:135], s[22:23], 0, v[150:151]
	s_nop 0
	v_addc_co_u32_e32 v131, vcc, 0, v131, vcc
	v_lshl_add_u64 v[198:199], s[22:23], 0, v[152:153]
	global_load_dwordx4 v[130:133], v[130:131], off nt
	v_lshl_add_u64 v[214:215], v[134:135], 0, v[176:177]
	v_lshl_add_u64 v[216:217], v[198:199], 0, v[176:177]
	global_load_dwordx4 v[182:185], v[214:215], off nt
	global_load_dwordx4 v[138:141], v[142:143], off offset:64 nt
	global_load_dwordx4 v[134:137], v[142:143], off offset:512 nt
	global_load_dwordx4 v[186:189], v[214:215], off offset:64 nt
	s_nop 0
	global_load_dwordx4 v[142:145], v[142:143], off offset:576 nt
	s_nop 0
	global_load_dwordx4 v[190:193], v[214:215], off offset:512 nt
	global_load_dwordx4 v[194:197], v[214:215], off offset:576 nt
	global_load_dwordx4 v[198:201], v[216:217], off nt
	global_load_dwordx4 v[202:205], v[216:217], off offset:64 nt
	global_load_dwordx4 v[206:209], v[216:217], off offset:512 nt
	global_load_dwordx4 v[210:213], v[216:217], off offset:576 nt
	v_lshl_add_u64 v[218:219], s[22:23], 0, v[154:155]
	v_lshl_add_u64 v[218:219], v[218:219], 0, v[176:177]
	s_andn2_b64 vcc, exec, s[0:1]
	s_mov_b64 s[0:1], -1
	s_waitcnt vmcnt(0)
	v_pk_fma_f32 v[124:125], v[124:125], v[140:141], v[188:189]
	v_pk_fma_f32 v[128:129], v[128:129], v[132:133], v[184:185]
	v_pk_fma_f32 v[126:127], v[126:127], v[130:131], v[182:183]
	v_pk_fma_f32 v[114:115], v[114:115], v[138:139], v[202:203]
	v_pk_fma_f32 v[122:123], v[122:123], v[138:139], v[186:187]
	v_pk_fma_f32 v[112:113], v[112:113], v[136:137], v[192:193]
	v_pk_fma_f32 v[110:111], v[110:111], v[134:135], v[190:191]
	v_pk_fma_f32 v[108:109], v[108:109], v[144:145], v[196:197]
	v_pk_fma_f32 v[106:107], v[106:107], v[142:143], v[194:195]
	v_pk_fma_f32 v[120:121], v[120:121], v[132:133], v[200:201]
	v_pk_fma_f32 v[118:119], v[118:119], v[130:131], v[198:199]
	v_pk_fma_f32 v[116:117], v[116:117], v[140:141], v[204:205]
	v_pk_fma_f32 v[104:105], v[104:105], v[136:137], v[208:209]
	v_pk_fma_f32 v[102:103], v[102:103], v[134:135], v[206:207]
	v_pk_fma_f32 v[100:101], v[100:101], v[144:145], v[212:213]
	v_pk_fma_f32 v[98:99], v[98:99], v[142:143], v[210:211]
	global_store_dwordx4 v[214:215], v[126:129], off nt
	global_store_dwordx4 v[214:215], v[122:125], off offset:64 nt
	global_store_dwordx4 v[214:215], v[110:113], off offset:512 nt
	global_store_dwordx4 v[214:215], v[106:109], off offset:576 nt
	global_store_dwordx4 v[216:217], v[118:121], off nt
	global_store_dwordx4 v[216:217], v[114:117], off offset:64 nt
	global_store_dwordx4 v[216:217], v[102:105], off offset:512 nt
	global_store_dwordx4 v[216:217], v[98:101], off offset:576 nt
	v_lshl_add_u64 v[114:115], s[22:23], 0, v[156:157]
	v_lshl_add_u64 v[182:183], v[114:115], 0, v[176:177]
	global_load_dwordx4 v[98:101], v[218:219], off nt
	global_load_dwordx4 v[102:105], v[218:219], off offset:64 nt
	global_load_dwordx4 v[106:109], v[218:219], off offset:512 nt
	global_load_dwordx4 v[110:113], v[218:219], off offset:576 nt
	global_load_dwordx4 v[114:117], v[182:183], off nt
	global_load_dwordx4 v[118:121], v[182:183], off offset:64 nt
	global_load_dwordx4 v[122:125], v[182:183], off offset:512 nt
	global_load_dwordx4 v[126:129], v[182:183], off offset:576 nt
	v_lshl_add_u64 v[184:185], s[22:23], 0, v[158:159]
	v_lshl_add_u64 v[184:185], v[184:185], 0, v[176:177]
	s_waitcnt vmcnt(7)
	v_pk_fma_f32 v[96:97], v[96:97], v[132:133], v[100:101]
	v_pk_fma_f32 v[94:95], v[94:95], v[130:131], v[98:99]
	s_waitcnt vmcnt(2)
	v_pk_fma_f32 v[82:83], v[82:83], v[138:139], v[118:119]
	v_pk_fma_f32 v[92:93], v[92:93], v[140:141], v[104:105]
	v_pk_fma_f32 v[90:91], v[90:91], v[138:139], v[102:103]
	v_pk_fma_f32 v[80:81], v[80:81], v[136:137], v[108:109]
	v_pk_fma_f32 v[78:79], v[78:79], v[134:135], v[106:107]
	v_pk_fma_f32 v[76:77], v[76:77], v[144:145], v[112:113]
	v_pk_fma_f32 v[74:75], v[74:75], v[142:143], v[110:111]
	v_pk_fma_f32 v[88:89], v[88:89], v[132:133], v[116:117]
	v_pk_fma_f32 v[86:87], v[86:87], v[130:131], v[114:115]
	v_pk_fma_f32 v[84:85], v[84:85], v[140:141], v[120:121]
	s_waitcnt vmcnt(1)
	v_pk_fma_f32 v[72:73], v[72:73], v[136:137], v[124:125]
	v_pk_fma_f32 v[70:71], v[70:71], v[134:135], v[122:123]
	s_waitcnt vmcnt(0)
	v_pk_fma_f32 v[68:69], v[68:69], v[144:145], v[128:129]
	v_pk_fma_f32 v[66:67], v[66:67], v[142:143], v[126:127]
	global_store_dwordx4 v[218:219], v[94:97], off nt
	global_store_dwordx4 v[218:219], v[90:93], off offset:64 nt
	global_store_dwordx4 v[218:219], v[78:81], off offset:512 nt
	global_store_dwordx4 v[218:219], v[74:77], off offset:576 nt
	global_store_dwordx4 v[182:183], v[86:89], off nt
	global_store_dwordx4 v[182:183], v[82:85], off offset:64 nt
	global_store_dwordx4 v[182:183], v[70:73], off offset:512 nt
	global_store_dwordx4 v[182:183], v[66:69], off offset:576 nt
	v_lshl_add_u64 v[82:83], s[22:23], 0, v[160:161]
	v_lshl_add_u64 v[98:99], v[82:83], 0, v[176:177]
	global_load_dwordx4 v[66:69], v[184:185], off nt
	global_load_dwordx4 v[70:73], v[184:185], off offset:64 nt
	global_load_dwordx4 v[74:77], v[184:185], off offset:512 nt
	global_load_dwordx4 v[78:81], v[184:185], off offset:576 nt
	global_load_dwordx4 v[82:85], v[98:99], off nt
	global_load_dwordx4 v[86:89], v[98:99], off offset:64 nt
	global_load_dwordx4 v[90:93], v[98:99], off offset:512 nt
	global_load_dwordx4 v[94:97], v[98:99], off offset:576 nt
	v_lshl_add_u64 v[100:101], s[22:23], 0, v[164:165]
	v_lshl_add_u64 v[100:101], v[100:101], 0, v[176:177]
	s_waitcnt vmcnt(7)
	v_pk_fma_f32 v[64:65], v[64:65], v[132:133], v[68:69]
	v_pk_fma_f32 v[62:63], v[62:63], v[130:131], v[66:67]
	s_waitcnt vmcnt(2)
	v_pk_fma_f32 v[50:51], v[50:51], v[138:139], v[86:87]
	v_pk_fma_f32 v[60:61], v[60:61], v[140:141], v[72:73]
	v_pk_fma_f32 v[58:59], v[58:59], v[138:139], v[70:71]
	v_pk_fma_f32 v[48:49], v[48:49], v[136:137], v[76:77]
	v_pk_fma_f32 v[46:47], v[46:47], v[134:135], v[74:75]
	v_pk_fma_f32 v[44:45], v[44:45], v[144:145], v[80:81]
	v_pk_fma_f32 v[42:43], v[42:43], v[142:143], v[78:79]
	v_pk_fma_f32 v[56:57], v[56:57], v[132:133], v[84:85]
	v_pk_fma_f32 v[54:55], v[54:55], v[130:131], v[82:83]
	v_pk_fma_f32 v[52:53], v[52:53], v[140:141], v[88:89]
	s_waitcnt vmcnt(1)
	v_pk_fma_f32 v[40:41], v[40:41], v[136:137], v[92:93]
	v_pk_fma_f32 v[38:39], v[38:39], v[134:135], v[90:91]
	s_waitcnt vmcnt(0)
	v_pk_fma_f32 v[36:37], v[36:37], v[144:145], v[96:97]
	v_pk_fma_f32 v[34:35], v[34:35], v[142:143], v[94:95]
	global_store_dwordx4 v[184:185], v[62:65], off nt
	global_store_dwordx4 v[184:185], v[58:61], off offset:64 nt
	global_store_dwordx4 v[184:185], v[46:49], off offset:512 nt
	global_store_dwordx4 v[184:185], v[42:45], off offset:576 nt
	global_store_dwordx4 v[98:99], v[54:57], off nt
	global_store_dwordx4 v[98:99], v[50:53], off offset:64 nt
	global_store_dwordx4 v[98:99], v[38:41], off offset:512 nt
	global_store_dwordx4 v[98:99], v[34:37], off offset:576 nt
	v_lshl_add_u64 v[50:51], s[22:23], 0, v[166:167]
	v_lshl_add_u64 v[66:67], v[50:51], 0, v[176:177]
	global_load_dwordx4 v[34:37], v[100:101], off nt
	global_load_dwordx4 v[38:41], v[100:101], off offset:64 nt
	global_load_dwordx4 v[42:45], v[100:101], off offset:512 nt
	global_load_dwordx4 v[46:49], v[100:101], off offset:576 nt
	global_load_dwordx4 v[50:53], v[66:67], off nt
	global_load_dwordx4 v[54:57], v[66:67], off offset:64 nt
	global_load_dwordx4 v[58:61], v[66:67], off offset:512 nt
	global_load_dwordx4 v[62:65], v[66:67], off offset:576 nt
	s_waitcnt vmcnt(7)
	v_pk_fma_f32 v[32:33], v[32:33], v[132:133], v[36:37]
	v_pk_fma_f32 v[30:31], v[30:31], v[130:131], v[34:35]
	s_waitcnt vmcnt(6)
	v_pk_fma_f32 v[28:29], v[28:29], v[140:141], v[40:41]
	v_pk_fma_f32 v[26:27], v[26:27], v[138:139], v[38:39]
	s_waitcnt vmcnt(5)
	v_pk_fma_f32 v[16:17], v[16:17], v[136:137], v[44:45]
	v_pk_fma_f32 v[14:15], v[14:15], v[134:135], v[42:43]
	s_waitcnt vmcnt(4)
	v_pk_fma_f32 v[12:13], v[12:13], v[144:145], v[48:49]
	v_pk_fma_f32 v[10:11], v[10:11], v[142:143], v[46:47]
	s_waitcnt vmcnt(3)
	v_pk_fma_f32 v[24:25], v[24:25], v[132:133], v[52:53]
	v_pk_fma_f32 v[22:23], v[22:23], v[130:131], v[50:51]
	s_waitcnt vmcnt(2)
	v_pk_fma_f32 v[20:21], v[20:21], v[140:141], v[56:57]
	v_pk_fma_f32 v[18:19], v[18:19], v[138:139], v[54:55]
	s_waitcnt vmcnt(1)
	v_pk_fma_f32 v[8:9], v[8:9], v[136:137], v[60:61]
	v_pk_fma_f32 v[6:7], v[6:7], v[134:135], v[58:59]
	s_waitcnt vmcnt(0)
	v_pk_fma_f32 v[4:5], v[4:5], v[144:145], v[64:65]
	v_pk_fma_f32 v[2:3], v[2:3], v[142:143], v[62:63]
	global_store_dwordx4 v[100:101], v[30:33], off nt
	global_store_dwordx4 v[100:101], v[26:29], off offset:64 nt
	global_store_dwordx4 v[100:101], v[14:17], off offset:512 nt
	global_store_dwordx4 v[100:101], v[10:13], off offset:576 nt
	global_store_dwordx4 v[66:67], v[22:25], off nt
	global_store_dwordx4 v[66:67], v[18:21], off offset:64 nt
	global_store_dwordx4 v[66:67], v[6:9], off offset:512 nt
	global_store_dwordx4 v[66:67], v[2:5], off offset:576 nt
	s_cbranch_vccnz .LBB0_1716
	s_andn2_b64 vcc, exec, s[6:7]
	s_cbranch_vccnz .LBB0_1715
	s_barrier
	s_branch .LBB0_1715
